# mlstm_a1/a3 unit prologues: the V tile row loads issued before the K tile is loaded and convolved (one exposed load latency less per unit)
# baseline (speedup 1.0000x reference)
.LBB0_367:
	s_or_b64 exec, exec, s[4:5]
	v_mov_b32_e32 v0, v192
	s_mul_i32 s0, s50, 0x3e00000
	s_mul_hi_i32 s1, s50, 0x3e00000
	s_add_u32 s0, s17, s0
	v_ashrrev_i32_e32 v81, 4, v0
	v_lshlrev_b32_e32 v0, 3, v0
	s_addc_u32 s1, s23, s1
	s_lshl_b32 s8, s49, 7
	v_and_b32_e32 v74, 0x78, v0
	v_or_b32_e32 v0, s8, v74
	v_add_u32_e32 v17, v81, v79
	v_lshlrev_b32_e32 v0, 1, v0
	v_lshl_add_u64 v[14:15], s[0:1], 0, v[0:1]
	v_lshrrev_b32_e32 v84, 4, v192
	v_add_u32_e32 v84, v84, v79
	v_mov_b64_e32 v[86:87], s[0:1]
	s_lshl_b32 s80, s8, 1
	s_mov_b32 s81, s9
	v_lshlrev_b32_e32 v88, 4, v192
	v_and_b32_e32 v88, 0xf0, v88
	v_mov_b32_e32 v89, 0
	v_mad_i64_i32 v[90:91], s[12:13], v84, s65, v[86:87]
	v_lshl_add_u64 v[90:91], v[90:91], 0, s[80:81]
	v_lshl_add_u64 v[90:91], v[90:91], 0, v[88:89]
	global_load_dwordx4 v[100:103], v[90:91], off offset:2048
	v_add_u32_e32 v85, 32, v84
	v_mad_i64_i32 v[90:91], s[12:13], v85, s65, v[86:87]
	v_lshl_add_u64 v[90:91], v[90:91], 0, s[80:81]
	v_lshl_add_u64 v[90:91], v[90:91], 0, v[88:89]
	global_load_dwordx4 v[104:107], v[90:91], off offset:2048
	v_add_u32_e32 v85, 64, v84
	v_mad_i64_i32 v[90:91], s[12:13], v85, s65, v[86:87]
	v_lshl_add_u64 v[90:91], v[90:91], 0, s[80:81]
	v_lshl_add_u64 v[90:91], v[90:91], 0, v[88:89]
	global_load_dwordx4 v[108:111], v[90:91], off offset:2048
	v_add_u32_e32 v85, 96, v84
	v_mad_i64_i32 v[90:91], s[12:13], v85, s65, v[86:87]
	v_lshl_add_u64 v[90:91], v[90:91], 0, s[80:81]
	v_lshl_add_u64 v[90:91], v[90:91], 0, v[88:89]
	global_load_dwordx4 v[112:115], v[90:91], off offset:2048
	v_mov_b32_e32 v62, 0
	v_cmp_lt_i32_e32 vcc, 0, v17
	v_mov_b32_e32 v66, 0
	v_mov_b32_e32 v67, 0
	v_mov_b32_e32 v68, 0
	v_mov_b32_e32 v69, 0
	s_and_saveexec_b64 s[4:5], vcc
	s_cbranch_execz .LBB0_369
	v_add_u32_e32 v0, -1, v17
	v_mad_u64_u32 v[2:3], s[18:19], v0, s65, v[14:15]
	global_load_dwordx4 v[66:69], v[2:3], off offset:1024

.LBB0_383:
	s_or_b64 exec, exec, s[4:5]
	s_lshl_b32 s4, s8, 2
	s_add_u32 s4, s2, s4
	s_addc_u32 s5, s30, 0
	v_lshlrev_b32_e32 v0, 2, v74
	v_lshl_add_u64 v[22:23], s[4:5], 0, v[0:1]
	v_lshrrev_b32_e32 v80, 4, v16
	global_load_dwordx4 v[14:17], v0, s[4:5] offset:2064
	global_load_dwordx4 v[26:29], v0, s[4:5] offset:2048
	s_mov_b64 s[4:5], 0x1800
	v_add_co_u32_e32 v20, vcc, s71, v22
	v_lshl_add_u64 v[18:19], v[22:23], 0, s[4:5]
	s_nop 0
	v_addc_co_u32_e32 v21, vcc, 0, v23, vcc
	s_mov_b64 s[4:5], 0x2800
	global_load_dwordx4 v[34:37], v[20:21], off offset:2048
	s_nop 0
	global_load_dwordx4 v[18:21], v[18:19], off offset:16
	v_lshl_add_u64 v[24:25], v[22:23], 0, s[4:5]
	v_add_co_u32_e32 v22, vcc, s64, v22
	s_waitcnt vmcnt(7)
	v_lshlrev_b32_e32 v82, 16, v70
	v_addc_co_u32_e32 v23, vcc, 0, v23, vcc
	global_load_dwordx4 v[42:45], v[22:23], off offset:2048
	s_nop 0
	global_load_dwordx4 v[22:25], v[24:25], off offset:16
	v_and_b32_e32 v83, 0xffff0000, v70
	v_lshlrev_b32_e32 v0, 1, v74
	v_lshlrev_b32_e32 v74, 16, v66
	v_and_b32_e32 v75, 0xffff0000, v66
	v_lshlrev_b32_e32 v70, 16, v71
	v_and_b32_e32 v71, 0xffff0000, v71
	v_lshlrev_b32_e32 v66, 16, v67
	v_and_b32_e32 v67, 0xffff0000, v67
	s_lshl_b32 s8, s8, 1
	s_xor_b32 s4, s48, 31
	v_and_b32_e32 v78, 15, v76
	s_waitcnt vmcnt(3)
	v_pk_mul_f32 v[82:83], v[34:35], v[82:83]
	s_nop 0
	v_pk_fma_f32 v[74:75], v[26:27], v[74:75], v[82:83]
	v_lshlrev_b32_e32 v82, 16, v62
	v_and_b32_e32 v83, 0xffff0000, v62
	v_pk_mul_f32 v[70:71], v[36:37], v[70:71]
	s_waitcnt vmcnt(1)
	v_pk_fma_f32 v[74:75], v[42:43], v[82:83], v[74:75]
	s_nop 0
	v_mul_f32_e32 v62, 0xbfb8aa3b, v74
	v_exp_f32_e32 v62, v62
	v_pk_fma_f32 v[66:67], v[28:29], v[66:67], v[70:71]
	v_lshlrev_b32_e32 v70, 16, v72
	v_and_b32_e32 v71, 0xffff0000, v72
	v_add_f32_e32 v62, 1.0, v62
	v_rcp_f32_e32 v82, v62
	v_mul_f32_e32 v62, 0xbfb8aa3b, v75
	v_exp_f32_e32 v62, v62
	v_pk_mul_f32 v[70:71], v[18:19], v[70:71]
	v_add_f32_e32 v62, 1.0, v62
	v_rcp_f32_e32 v83, v62
	v_lshlrev_b32_e32 v62, 16, v63
	v_and_b32_e32 v63, 0xffff0000, v63
	v_pk_fma_f32 v[62:63], v[44:45], v[62:63], v[66:67]
	v_pk_mul_f32 v[74:75], v[74:75], v[82:83]
	v_mul_f32_e32 v66, 0xbfb8aa3b, v62
	v_mul_f32_e32 v67, 0xbfb8aa3b, v63
	v_exp_f32_e32 v66, v66
	v_exp_f32_e32 v67, v67
	v_pk_mul_f32 v[74:75], v[74:75], s[22:23] op_sel_hi:[1,0]
	v_add_f32_e32 v66, 1.0, v66
	v_add_f32_e32 v67, 1.0, v67
	v_rcp_f32_e32 v66, v66
	v_rcp_f32_e32 v67, v67
	s_nop 0
	v_pk_mul_f32 v[62:63], v[62:63], v[66:67]
	v_lshlrev_b32_e32 v66, 16, v68
	v_and_b32_e32 v67, 0xffff0000, v68
	v_pk_fma_f32 v[66:67], v[14:15], v[66:67], v[70:71]
	v_lshlrev_b32_e32 v70, 16, v64
	v_and_b32_e32 v71, 0xffff0000, v64
	s_waitcnt vmcnt(0)
	v_pk_fma_f32 v[66:67], v[22:23], v[70:71], v[66:67]
	v_lshlrev_b32_e32 v68, 16, v69
	v_mul_f32_e32 v64, 0xbfb8aa3b, v66
	v_exp_f32_e32 v64, v64
	v_and_b32_e32 v69, 0xffff0000, v69
	v_pk_mul_f32 v[62:63], v[62:63], s[22:23] op_sel_hi:[1,0]
	v_add_f32_e32 v64, 1.0, v64
	v_rcp_f32_e32 v70, v64
	v_mul_f32_e32 v64, 0xbfb8aa3b, v67
	v_exp_f32_e32 v64, v64
	s_nop 0
	v_add_f32_e32 v64, 1.0, v64
	v_rcp_f32_e32 v71, v64
	v_lshlrev_b32_e32 v64, 16, v65
	v_and_b32_e32 v65, 0xffff0000, v65
	v_pk_mul_f32 v[66:67], v[66:67], v[70:71]
	v_lshlrev_b32_e32 v70, 16, v73
	v_and_b32_e32 v71, 0xffff0000, v73
	v_pk_mul_f32 v[70:71], v[20:21], v[70:71]
	v_pk_mul_f32 v[66:67], v[66:67], s[22:23] op_sel_hi:[1,0]
	v_pk_fma_f32 v[68:69], v[16:17], v[68:69], v[70:71]
	v_cvt_pk_bf16_f32 v66, v66, v67
	v_pk_fma_f32 v[64:65], v[24:25], v[64:65], v[68:69]
	s_nop 0
	v_mul_f32_e32 v68, 0xbfb8aa3b, v64
	v_mul_f32_e32 v69, 0xbfb8aa3b, v65
	v_exp_f32_e32 v68, v68
	v_exp_f32_e32 v69, v69
	v_add_f32_e32 v68, 1.0, v68
	v_add_f32_e32 v69, 1.0, v69
	v_rcp_f32_e32 v68, v68
	v_rcp_f32_e32 v69, v69
	s_nop 0
	v_pk_mul_f32 v[64:65], v[64:65], v[68:69]
	s_nop 0
	v_pk_mul_f32 v[68:69], v[64:65], s[22:23] op_sel_hi:[1,0]
	v_cvt_pk_bf16_f32 v65, v62, v63
	v_mul_lo_u32 v62, v81, s21
	v_cvt_pk_bf16_f32 v64, v74, v75
	v_cvt_pk_bf16_f32 v67, v68, v69
	v_add3_u32 v0, 0, v0, v62
	ds_write_b128 v0, v[64:67]
	v_lshlrev_b32_e32 v64, 16, v58
	v_and_b32_e32 v65, 0xffff0000, v58
	v_lshlrev_b32_e32 v62, 16, v54
	v_and_b32_e32 v63, 0xffff0000, v54
	v_pk_mul_f32 v[64:65], v[34:35], v[64:65]
	v_lshlrev_b32_e32 v58, 16, v59
	v_pk_fma_f32 v[62:63], v[26:27], v[62:63], v[64:65]
	v_lshlrev_b32_e32 v64, 16, v50
	v_and_b32_e32 v65, 0xffff0000, v50
	v_pk_fma_f32 v[62:63], v[42:43], v[64:65], v[62:63]
	v_and_b32_e32 v59, 0xffff0000, v59
	v_mul_f32_e32 v50, 0xbfb8aa3b, v62
	v_exp_f32_e32 v50, v50
	v_lshlrev_b32_e32 v54, 16, v55
	v_and_b32_e32 v55, 0xffff0000, v55
	v_pk_mul_f32 v[58:59], v[36:37], v[58:59]
	v_add_f32_e32 v50, 1.0, v50
	v_rcp_f32_e32 v64, v50
	v_mul_f32_e32 v50, 0xbfb8aa3b, v63
	v_exp_f32_e32 v50, v50
	v_pk_fma_f32 v[54:55], v[28:29], v[54:55], v[58:59]
	v_lshlrev_b32_e32 v58, 16, v60
	v_and_b32_e32 v59, 0xffff0000, v60
	v_add_f32_e32 v50, 1.0, v50
	v_rcp_f32_e32 v65, v50
	v_lshlrev_b32_e32 v50, 16, v51
	v_and_b32_e32 v51, 0xffff0000, v51
	v_pk_fma_f32 v[50:51], v[44:45], v[50:51], v[54:55]
	v_pk_mul_f32 v[58:59], v[18:19], v[58:59]
	v_mul_f32_e32 v54, 0xbfb8aa3b, v50
	v_mul_f32_e32 v55, 0xbfb8aa3b, v51
	v_exp_f32_e32 v54, v54
	v_exp_f32_e32 v55, v55
	v_pk_mul_f32 v[62:63], v[62:63], v[64:65]
	v_add_f32_e32 v54, 1.0, v54
	v_add_f32_e32 v55, 1.0, v55
	v_rcp_f32_e32 v54, v54
	v_rcp_f32_e32 v55, v55
	v_pk_mul_f32 v[62:63], v[62:63], s[22:23] op_sel_hi:[1,0]
	v_pk_mul_f32 v[50:51], v[50:51], v[54:55]
	s_nop 0
	v_pk_mul_f32 v[54:55], v[50:51], s[22:23] op_sel_hi:[1,0]
	v_lshlrev_b32_e32 v50, 16, v56
	v_and_b32_e32 v51, 0xffff0000, v56
	v_pk_fma_f32 v[50:51], v[14:15], v[50:51], v[58:59]
	v_lshlrev_b32_e32 v58, 16, v52
	v_and_b32_e32 v59, 0xffff0000, v52
	v_pk_fma_f32 v[50:51], v[22:23], v[58:59], v[50:51]
	v_lshlrev_b32_e32 v56, 16, v61
	v_mul_f32_e32 v52, 0xbfb8aa3b, v50
	v_exp_f32_e32 v52, v52
	s_nop 0
	v_add_f32_e32 v52, 1.0, v52
	v_rcp_f32_e32 v58, v52
	v_mul_f32_e32 v52, 0xbfb8aa3b, v51
	v_exp_f32_e32 v52, v52
	s_nop 0
	v_add_f32_e32 v52, 1.0, v52
	v_rcp_f32_e32 v59, v52
	v_lshlrev_b32_e32 v52, 16, v53
	v_and_b32_e32 v53, 0xffff0000, v53
	v_pk_mul_f32 v[50:51], v[50:51], v[58:59]
	s_nop 0
	v_pk_mul_f32 v[58:59], v[50:51], s[22:23] op_sel_hi:[1,0]
	v_lshlrev_b32_e32 v50, 16, v57
	v_and_b32_e32 v51, 0xffff0000, v57
	v_and_b32_e32 v57, 0xffff0000, v61
	v_pk_mul_f32 v[56:57], v[20:21], v[56:57]
	s_nop 0
	v_pk_fma_f32 v[50:51], v[16:17], v[50:51], v[56:57]
	s_nop 0
	v_pk_fma_f32 v[50:51], v[24:25], v[52:53], v[50:51]
	s_nop 0
	v_mul_f32_e32 v52, 0xbfb8aa3b, v50
	v_mul_f32_e32 v53, 0xbfb8aa3b, v51
	v_exp_f32_e32 v52, v52
	v_exp_f32_e32 v53, v53
	v_add_f32_e32 v52, 1.0, v52
	v_add_f32_e32 v53, 1.0, v53
	v_rcp_f32_e32 v52, v52
	v_rcp_f32_e32 v53, v53
	s_nop 0
	v_pk_mul_f32 v[50:51], v[50:51], v[52:53]
	s_nop 0
	v_pk_mul_f32 v[56:57], v[50:51], s[22:23] op_sel_hi:[1,0]
	v_cvt_pk_bf16_f32 v50, v62, v63
	v_cvt_pk_bf16_f32 v51, v54, v55
	v_cvt_pk_bf16_f32 v52, v58, v59
	v_cvt_pk_bf16_f32 v53, v56, v57
	ds_write_b128 v0, v[50:53] offset:9216
	v_lshlrev_b32_e32 v52, 16, v46
	v_and_b32_e32 v53, 0xffff0000, v46
	v_lshlrev_b32_e32 v50, 16, v38
	v_and_b32_e32 v51, 0xffff0000, v38
	v_pk_mul_f32 v[52:53], v[34:35], v[52:53]
	v_lshlrev_b32_e32 v46, 16, v47
	v_pk_fma_f32 v[50:51], v[26:27], v[50:51], v[52:53]
	v_lshlrev_b32_e32 v52, 16, v30
	v_and_b32_e32 v53, 0xffff0000, v30
	v_pk_fma_f32 v[50:51], v[42:43], v[52:53], v[50:51]
	v_and_b32_e32 v47, 0xffff0000, v47
	v_mul_f32_e32 v30, 0xbfb8aa3b, v50
	v_exp_f32_e32 v30, v30
	v_lshlrev_b32_e32 v38, 16, v39
	v_and_b32_e32 v39, 0xffff0000, v39
	v_pk_mul_f32 v[46:47], v[36:37], v[46:47]
	v_add_f32_e32 v30, 1.0, v30
	v_rcp_f32_e32 v52, v30
	v_mul_f32_e32 v30, 0xbfb8aa3b, v51
	v_exp_f32_e32 v30, v30
	v_pk_fma_f32 v[38:39], v[28:29], v[38:39], v[46:47]
	v_lshlrev_b32_e32 v46, 16, v48
	v_and_b32_e32 v47, 0xffff0000, v48
	v_add_f32_e32 v30, 1.0, v30
	v_rcp_f32_e32 v53, v30
	v_lshlrev_b32_e32 v30, 16, v31
	v_and_b32_e32 v31, 0xffff0000, v31
	v_pk_fma_f32 v[30:31], v[44:45], v[30:31], v[38:39]
	v_pk_mul_f32 v[46:47], v[18:19], v[46:47]
	v_mul_f32_e32 v38, 0xbfb8aa3b, v30
	v_mul_f32_e32 v39, 0xbfb8aa3b, v31
	v_exp_f32_e32 v38, v38
	v_exp_f32_e32 v39, v39
	v_pk_mul_f32 v[50:51], v[50:51], v[52:53]
	v_add_f32_e32 v38, 1.0, v38
	v_add_f32_e32 v39, 1.0, v39
	v_rcp_f32_e32 v38, v38
	v_rcp_f32_e32 v39, v39
	v_pk_mul_f32 v[50:51], v[50:51], s[22:23] op_sel_hi:[1,0]
	v_pk_mul_f32 v[30:31], v[30:31], v[38:39]
	s_nop 0
	v_pk_mul_f32 v[38:39], v[30:31], s[22:23] op_sel_hi:[1,0]
	v_lshlrev_b32_e32 v30, 16, v40
	v_and_b32_e32 v31, 0xffff0000, v40
	v_pk_fma_f32 v[30:31], v[14:15], v[30:31], v[46:47]
	v_lshlrev_b32_e32 v46, 16, v32
	v_and_b32_e32 v47, 0xffff0000, v32
	v_pk_fma_f32 v[30:31], v[22:23], v[46:47], v[30:31]
	v_lshlrev_b32_e32 v40, 16, v49
	v_mul_f32_e32 v32, 0xbfb8aa3b, v30
	v_exp_f32_e32 v32, v32
	s_nop 0
	v_add_f32_e32 v32, 1.0, v32
	v_rcp_f32_e32 v46, v32
	v_mul_f32_e32 v32, 0xbfb8aa3b, v31
	v_exp_f32_e32 v32, v32
	s_nop 0
	v_add_f32_e32 v32, 1.0, v32
	v_rcp_f32_e32 v47, v32
	v_lshlrev_b32_e32 v32, 16, v33
	v_and_b32_e32 v33, 0xffff0000, v33
	v_pk_mul_f32 v[30:31], v[30:31], v[46:47]
	s_nop 0
	v_pk_mul_f32 v[46:47], v[30:31], s[22:23] op_sel_hi:[1,0]
	v_lshlrev_b32_e32 v30, 16, v41
	v_and_b32_e32 v31, 0xffff0000, v41
	v_and_b32_e32 v41, 0xffff0000, v49
	v_pk_mul_f32 v[40:41], v[20:21], v[40:41]
	s_nop 0
	v_pk_fma_f32 v[30:31], v[16:17], v[30:31], v[40:41]
	s_nop 0
	v_pk_fma_f32 v[30:31], v[24:25], v[32:33], v[30:31]
	s_nop 0
	v_mul_f32_e32 v32, 0xbfb8aa3b, v30
	v_mul_f32_e32 v33, 0xbfb8aa3b, v31
	v_exp_f32_e32 v32, v32
	v_exp_f32_e32 v33, v33
	v_add_f32_e32 v32, 1.0, v32
	v_add_f32_e32 v33, 1.0, v33
	v_rcp_f32_e32 v32, v32
	v_rcp_f32_e32 v33, v33
	s_nop 0
	v_pk_mul_f32 v[30:31], v[30:31], v[32:33]
	s_nop 0
	v_pk_mul_f32 v[40:41], v[30:31], s[22:23] op_sel_hi:[1,0]
	v_cvt_pk_bf16_f32 v30, v50, v51
	v_cvt_pk_bf16_f32 v31, v38, v39
	v_cvt_pk_bf16_f32 v32, v46, v47
	v_cvt_pk_bf16_f32 v33, v40, v41
	ds_write_b128 v0, v[30:33] offset:18432
	v_lshlrev_b32_e32 v32, 16, v10
	v_and_b32_e32 v33, 0xffff0000, v10
	v_lshlrev_b32_e32 v30, 16, v6
	v_and_b32_e32 v31, 0xffff0000, v6
	v_pk_mul_f32 v[32:33], v[34:35], v[32:33]
	v_lshlrev_b32_e32 v10, 16, v11
	v_pk_fma_f32 v[26:27], v[26:27], v[30:31], v[32:33]
	v_lshlrev_b32_e32 v30, 16, v2
	v_and_b32_e32 v31, 0xffff0000, v2
	v_pk_fma_f32 v[26:27], v[42:43], v[30:31], v[26:27]
	v_and_b32_e32 v11, 0xffff0000, v11
	v_mul_f32_e32 v2, 0xbfb8aa3b, v26
	v_exp_f32_e32 v2, v2
	v_lshlrev_b32_e32 v6, 16, v7
	v_and_b32_e32 v7, 0xffff0000, v7
	v_pk_mul_f32 v[10:11], v[36:37], v[10:11]
	v_add_f32_e32 v2, 1.0, v2
	v_rcp_f32_e32 v30, v2
	v_mul_f32_e32 v2, 0xbfb8aa3b, v27
	v_exp_f32_e32 v2, v2
	v_pk_fma_f32 v[6:7], v[28:29], v[6:7], v[10:11]
	v_lshlrev_b32_e32 v10, 16, v12
	v_and_b32_e32 v11, 0xffff0000, v12
	v_add_f32_e32 v2, 1.0, v2
	v_rcp_f32_e32 v31, v2
	v_lshlrev_b32_e32 v2, 16, v3
	v_and_b32_e32 v3, 0xffff0000, v3
	v_pk_fma_f32 v[2:3], v[44:45], v[2:3], v[6:7]
	v_pk_mul_f32 v[10:11], v[18:19], v[10:11]
	v_mul_f32_e32 v6, 0xbfb8aa3b, v2
	v_mul_f32_e32 v7, 0xbfb8aa3b, v3
	v_exp_f32_e32 v6, v6
	v_exp_f32_e32 v7, v7
	v_pk_mul_f32 v[26:27], v[26:27], v[30:31]
	v_add_f32_e32 v6, 1.0, v6
	v_add_f32_e32 v7, 1.0, v7
	v_rcp_f32_e32 v6, v6
	v_rcp_f32_e32 v7, v7
	v_pk_mul_f32 v[26:27], v[26:27], s[22:23] op_sel_hi:[1,0]
	v_pk_mul_f32 v[2:3], v[2:3], v[6:7]
	s_nop 0
	v_pk_mul_f32 v[6:7], v[2:3], s[22:23] op_sel_hi:[1,0]
	v_lshlrev_b32_e32 v2, 16, v8
	v_and_b32_e32 v3, 0xffff0000, v8
	v_pk_fma_f32 v[2:3], v[14:15], v[2:3], v[10:11]
	v_lshlrev_b32_e32 v10, 16, v4
	v_and_b32_e32 v11, 0xffff0000, v4
	v_pk_fma_f32 v[2:3], v[22:23], v[10:11], v[2:3]
	v_lshlrev_b32_e32 v8, 16, v13
	v_mul_f32_e32 v4, 0xbfb8aa3b, v2
	v_exp_f32_e32 v4, v4
	v_mov_b64_e32 v[14:15], s[0:1]
	v_add_f32_e32 v4, 1.0, v4
	v_rcp_f32_e32 v10, v4
	v_mul_f32_e32 v4, 0xbfb8aa3b, v3
	v_exp_f32_e32 v4, v4
	s_nop 0
	v_add_f32_e32 v4, 1.0, v4
	v_rcp_f32_e32 v11, v4
	v_lshlrev_b32_e32 v4, 16, v5
	v_and_b32_e32 v5, 0xffff0000, v5
	v_pk_mul_f32 v[2:3], v[2:3], v[10:11]
	s_nop 0
	v_pk_mul_f32 v[10:11], v[2:3], s[22:23] op_sel_hi:[1,0]
	v_lshlrev_b32_e32 v2, 16, v9
	v_and_b32_e32 v3, 0xffff0000, v9
	v_and_b32_e32 v9, 0xffff0000, v13
	v_pk_mul_f32 v[8:9], v[20:21], v[8:9]
	s_nop 0
	v_pk_fma_f32 v[2:3], v[16:17], v[2:3], v[8:9]
	s_nop 0
	v_pk_fma_f32 v[2:3], v[24:25], v[4:5], v[2:3]
	s_nop 0
	v_mul_f32_e32 v4, 0xbfb8aa3b, v2
	v_mul_f32_e32 v5, 0xbfb8aa3b, v3
	v_exp_f32_e32 v4, v4
	v_exp_f32_e32 v5, v5
	v_add_f32_e32 v4, 1.0, v4
	v_add_f32_e32 v5, 1.0, v5
	v_rcp_f32_e32 v4, v4
	v_rcp_f32_e32 v5, v5
	s_nop 0
	v_pk_mul_f32 v[2:3], v[2:3], v[4:5]
	s_nop 0
	v_pk_mul_f32 v[8:9], v[2:3], s[22:23] op_sel_hi:[1,0]
	v_cvt_pk_bf16_f32 v2, v26, v27
	v_cvt_pk_bf16_f32 v3, v6, v7
	v_cvt_pk_bf16_f32 v4, v10, v11
	v_cvt_pk_bf16_f32 v5, v8, v9
	ds_write_b128 v0, v[2:5] offset:27648
	v_mov_b32_e32 v0, v192
	s_nop 0
	v_ashrrev_i32_e32 v18, 4, v0
	v_lshlrev_b32_e32 v0, 4, v0
	v_and_b32_e32 v0, 0xf0, v0
	v_mul_lo_u32 v18, v18, s21
	v_add3_u32 v0, 0, v0, v18
	s_waitcnt vmcnt(3)
	ds_write_b128 v0, v[100:103] offset:36864
	s_waitcnt vmcnt(2)
	ds_write_b128 v0, v[104:107] offset:46080
	s_waitcnt vmcnt(1)
	ds_write_b128 v0, v[108:111] offset:55296
	s_waitcnt vmcnt(0)
	ds_write_b128 v0, v[112:115] offset:64512
	v_lshlrev_b32_e32 v2, 3, v76
	v_and_b32_e32 v2, 24, v2
	v_lshlrev_b32_e32 v0, 3, v80
	v_bfe_u32 v3, v76, 2, 2
	v_add_u32_e32 v2, 0, v2
	v_lshl_add_u32 v4, v77, 5, v2
	v_or_b32_e32 v5, v0, v3
	v_mad_u32_u24 v6, v5, s21, v4
	s_add_i32 s0, 0, 0x12000
	v_lshlrev_b32_e32 v14, 5, v80
	s_waitcnt lgkmcnt(0)
	s_barrier
	ds_read_b64_tr_b16 v[22:23], v6
	ds_read_b64_tr_b16 v[24:25], v6 offset:1152
	v_add_u32_e32 v10, s0, v14
	ds_read_b128 v[6:9], v10
	ds_read_b128 v[10:13], v10 offset:16
	v_add_u32_e32 v18, s28, v14
	ds_read_b128 v[14:17], v18
	ds_read_b128 v[18:21], v18 offset:16
	s_waitcnt lgkmcnt(5)
	v_lshlrev_b32_e32 v26, 16, v22
	v_and_b32_e32 v27, 0xffff0000, v22
	v_lshlrev_b32_e32 v22, 16, v23
	v_and_b32_e32 v23, 0xffff0000, v23
	s_waitcnt lgkmcnt(3)
	v_pk_mul_f32 v[6:7], v[6:7], v[26:27]
	v_pk_mul_f32 v[8:9], v[8:9], v[22:23]
	v_cvt_pk_bf16_f32 v6, v6, v7
	s_waitcnt lgkmcnt(1)
	v_pk_mul_f32 v[14:15], v[14:15], v[26:27]
	v_cvt_pk_bf16_f32 v7, v8, v9
	v_pk_mul_f32 v[8:9], v[16:17], v[22:23]
	v_lshlrev_b32_e32 v16, 16, v24
	v_and_b32_e32 v17, 0xffff0000, v24
	v_cvt_pk_bf16_f32 v14, v14, v15
	v_cvt_pk_bf16_f32 v15, v8, v9
	v_pk_mul_f32 v[8:9], v[10:11], v[16:17]
	s_waitcnt lgkmcnt(0)
	v_pk_mul_f32 v[10:11], v[18:19], v[16:17]
	v_mad_u32_u24 v5, v5, s21, v2
	v_cvt_pk_bf16_f32 v16, v10, v11
	v_lshlrev_b32_e32 v10, 16, v25
	v_and_b32_e32 v11, 0xffff0000, v25
	v_pk_mul_f32 v[12:13], v[12:13], v[10:11]
	v_pk_mul_f32 v[10:11], v[20:21], v[10:11]
	v_cvt_pk_bf16_f32 v8, v8, v9
	v_cvt_pk_bf16_f32 v9, v12, v13
	v_cvt_pk_bf16_f32 v17, v10, v11
	ds_read_b64_tr_b16 v[12:13], v5 offset:38016
	ds_read_b64_tr_b16 v[10:11], v5 offset:36864
	ds_read_b64_tr_b16 v[18:19], v5 offset:36896
	ds_read_b64_tr_b16 v[20:21], v5 offset:38048
	ds_read_b64_tr_b16 v[30:31], v5 offset:36928
	ds_read_b64_tr_b16 v[32:33], v5 offset:38080
	ds_read_b64_tr_b16 v[38:39], v5 offset:36960
	ds_read_b64_tr_b16 v[40:41], v5 offset:38112
	ds_read_b64_tr_b16 v[46:47], v5 offset:36992
	ds_read_b64_tr_b16 v[48:49], v5 offset:38144
	ds_read_b64_tr_b16 v[54:55], v5 offset:37024
	ds_read_b64_tr_b16 v[56:57], v5 offset:38176
	ds_read_b64_tr_b16 v[62:63], v5 offset:37056
	ds_read_b64_tr_b16 v[64:65], v5 offset:38208
	ds_read_b64_tr_b16 v[70:71], v5 offset:37088
	ds_read_b64_tr_b16 v[72:73], v5 offset:38240
	v_or_b32_e32 v5, 32, v0
	v_or_b32_e32 v79, v5, v3
	s_waitcnt lgkmcnt(14)
	v_mfma_f32_16x16x32_bf16 v[22:25], v[6:9], v[10:13], 0
	v_lshlrev_b32_e32 v5, 2, v5
	v_add_u32_e32 v80, s0, v5
	v_add_u32_e32 v5, s28, v5
	v_mfma_f32_16x16x32_bf16 v[10:13], v[14:17], v[10:13], 0
	s_lshl_b32 s1, s49, 1
	s_waitcnt lgkmcnt(12)
	v_mfma_f32_16x16x32_bf16 v[26:29], v[6:9], v[18:21], 0
	v_mfma_f32_16x16x32_bf16 v[18:21], v[14:17], v[18:21], 0
	s_waitcnt lgkmcnt(10)
	v_mfma_f32_16x16x32_bf16 v[34:37], v[6:9], v[30:33], 0
	v_mfma_f32_16x16x32_bf16 v[30:33], v[14:17], v[30:33], 0
	s_waitcnt lgkmcnt(8)
	v_mfma_f32_16x16x32_bf16 v[42:45], v[6:9], v[38:41], 0
	v_mfma_f32_16x16x32_bf16 v[38:41], v[14:17], v[38:41], 0
	s_waitcnt lgkmcnt(6)
	v_mfma_f32_16x16x32_bf16 v[50:53], v[6:9], v[46:49], 0
	v_mfma_f32_16x16x32_bf16 v[46:49], v[14:17], v[46:49], 0
	s_waitcnt lgkmcnt(4)
	v_mfma_f32_16x16x32_bf16 v[58:61], v[6:9], v[54:57], 0
	v_mfma_f32_16x16x32_bf16 v[54:57], v[14:17], v[54:57], 0
	s_waitcnt lgkmcnt(2)
	v_mfma_f32_16x16x32_bf16 v[66:69], v[6:9], v[62:65], 0
	v_mfma_f32_16x16x32_bf16 v[62:65], v[14:17], v[62:65], 0
	s_waitcnt lgkmcnt(0)
	v_mfma_f32_16x16x32_bf16 v[6:9], v[6:9], v[70:73], 0
	v_mfma_f32_16x16x32_bf16 v[14:17], v[14:17], v[70:73], 0
	v_mad_u32_u24 v70, v79, s21, v4
	ds_read_b64_tr_b16 v[74:75], v70
	ds_read_b64_tr_b16 v[92:93], v70 offset:1152
	ds_read_b128 v[70:73], v80
	ds_read_b128 v[80:83], v80 offset:16
	ds_read_b128 v[84:87], v5
	ds_read_b128 v[88:91], v5 offset:16
	v_mad_u32_u24 v5, v79, s21, v2
	s_waitcnt lgkmcnt(5)
	v_lshlrev_b32_e32 v94, 16, v74
	v_and_b32_e32 v95, 0xffff0000, v74
	v_lshlrev_b32_e32 v74, 16, v75
	v_and_b32_e32 v75, 0xffff0000, v75
	s_waitcnt lgkmcnt(3)
	v_pk_mul_f32 v[70:71], v[70:71], v[94:95]
	v_pk_mul_f32 v[72:73], v[72:73], v[74:75]
	v_cvt_pk_bf16_f32 v70, v70, v71
	s_waitcnt lgkmcnt(1)
	v_pk_mul_f32 v[84:85], v[84:85], v[94:95]
	v_cvt_pk_bf16_f32 v71, v72, v73
	v_pk_mul_f32 v[72:73], v[86:87], v[74:75]
	v_lshlrev_b32_e32 v74, 16, v92
	v_and_b32_e32 v75, 0xffff0000, v92
	v_cvt_pk_bf16_f32 v84, v84, v85
	v_cvt_pk_bf16_f32 v85, v72, v73
	v_pk_mul_f32 v[72:73], v[80:81], v[74:75]
	s_waitcnt lgkmcnt(0)
	v_pk_mul_f32 v[74:75], v[88:89], v[74:75]
	v_cvt_pk_bf16_f32 v72, v72, v73
	v_cvt_pk_bf16_f32 v86, v74, v75
	v_lshlrev_b32_e32 v74, 16, v93
	v_and_b32_e32 v75, 0xffff0000, v93
	v_pk_mul_f32 v[80:81], v[82:83], v[74:75]
	v_pk_mul_f32 v[74:75], v[90:91], v[74:75]
	v_cvt_pk_bf16_f32 v73, v80, v81
	v_cvt_pk_bf16_f32 v87, v74, v75
	ds_read_b64_tr_b16 v[82:83], v5 offset:38016
	ds_read_b64_tr_b16 v[80:81], v5 offset:36864
	ds_read_b64_tr_b16 v[88:89], v5 offset:36896
	s_waitcnt lgkmcnt(1)
	v_mfma_f32_16x16x32_bf16 v[22:25], v[70:73], v[80:83], v[22:25]
	ds_read_b64_tr_b16 v[90:91], v5 offset:38048
	v_mfma_f32_16x16x32_bf16 v[10:13], v[84:87], v[80:83], v[10:13]
	ds_read_b64_tr_b16 v[80:81], v5 offset:36928
	ds_read_b64_tr_b16 v[82:83], v5 offset:38080
	s_waitcnt lgkmcnt(0)
	v_mfma_f32_16x16x32_bf16 v[34:37], v[70:73], v[80:83], v[34:37]
	v_mfma_f32_16x16x32_bf16 v[30:33], v[84:87], v[80:83], v[30:33]
	ds_read_b64_tr_b16 v[80:81], v5 offset:36960
	ds_read_b64_tr_b16 v[82:83], v5 offset:38112
	s_waitcnt lgkmcnt(0)
	v_mfma_f32_16x16x32_bf16 v[42:45], v[70:73], v[80:83], v[42:45]
	v_mfma_f32_16x16x32_bf16 v[38:41], v[84:87], v[80:83], v[38:41]
	ds_read_b64_tr_b16 v[80:81], v5 offset:36992
	ds_read_b64_tr_b16 v[82:83], v5 offset:38144
	s_waitcnt lgkmcnt(0)
	v_mfma_f32_16x16x32_bf16 v[50:53], v[70:73], v[80:83], v[50:53]
	v_mfma_f32_16x16x32_bf16 v[46:49], v[84:87], v[80:83], v[46:49]
	ds_read_b64_tr_b16 v[80:81], v5 offset:37024
	ds_read_b64_tr_b16 v[82:83], v5 offset:38176
	s_waitcnt lgkmcnt(0)
	v_mfma_f32_16x16x32_bf16 v[58:61], v[70:73], v[80:83], v[58:61]
	v_mfma_f32_16x16x32_bf16 v[54:57], v[84:87], v[80:83], v[54:57]
	ds_read_b64_tr_b16 v[80:81], v5 offset:37056
	ds_read_b64_tr_b16 v[82:83], v5 offset:38208
	s_waitcnt lgkmcnt(0)
	v_mfma_f32_16x16x32_bf16 v[66:69], v[70:73], v[80:83], v[66:69]
	v_mfma_f32_16x16x32_bf16 v[62:65], v[84:87], v[80:83], v[62:65]
	ds_read_b64_tr_b16 v[80:81], v5 offset:37088
	ds_read_b64_tr_b16 v[82:83], v5 offset:38240
	v_or_b32_e32 v5, 64, v0
	v_or_b32_e32 v79, v5, v3
	v_mfma_f32_16x16x32_bf16 v[26:29], v[70:73], v[88:91], v[26:29]
	v_lshlrev_b32_e32 v5, 2, v5
	s_waitcnt lgkmcnt(0)
	v_mfma_f32_16x16x32_bf16 v[6:9], v[70:73], v[80:83], v[6:9]
	v_mad_u32_u24 v70, v79, s21, v4
	ds_read_b64_tr_b16 v[74:75], v70
	ds_read_b64_tr_b16 v[92:93], v70 offset:1152
	s_waitcnt lgkmcnt(1)
	v_lshlrev_b32_e32 v94, 16, v74
	v_mfma_f32_16x16x32_bf16 v[14:17], v[84:87], v[80:83], v[14:17]
	v_add_u32_e32 v80, s0, v5
	ds_read_b128 v[70:73], v80
	ds_read_b128 v[80:83], v80 offset:16
	v_add_u32_e32 v5, s28, v5
	v_mfma_f32_16x16x32_bf16 v[18:21], v[84:87], v[88:91], v[18:21]
	ds_read_b128 v[84:87], v5
	ds_read_b128 v[88:91], v5 offset:16
	v_and_b32_e32 v95, 0xffff0000, v74
	v_lshlrev_b32_e32 v74, 16, v75
	v_and_b32_e32 v75, 0xffff0000, v75
	s_waitcnt lgkmcnt(3)
	v_pk_mul_f32 v[70:71], v[70:71], v[94:95]
	v_pk_mul_f32 v[72:73], v[72:73], v[74:75]
	v_cvt_pk_bf16_f32 v70, v70, v71
	s_waitcnt lgkmcnt(1)
	v_pk_mul_f32 v[84:85], v[84:85], v[94:95]
	v_cvt_pk_bf16_f32 v71, v72, v73
	v_pk_mul_f32 v[72:73], v[86:87], v[74:75]
	v_lshlrev_b32_e32 v74, 16, v92
	v_and_b32_e32 v75, 0xffff0000, v92
	v_cvt_pk_bf16_f32 v84, v84, v85
	v_cvt_pk_bf16_f32 v85, v72, v73
	v_pk_mul_f32 v[72:73], v[80:81], v[74:75]
	s_waitcnt lgkmcnt(0)
	v_pk_mul_f32 v[74:75], v[88:89], v[74:75]
	v_cvt_pk_bf16_f32 v72, v72, v73
	v_cvt_pk_bf16_f32 v86, v74, v75
	v_lshlrev_b32_e32 v74, 16, v93
	v_and_b32_e32 v75, 0xffff0000, v93
	v_pk_mul_f32 v[80:81], v[82:83], v[74:75]
	v_pk_mul_f32 v[74:75], v[90:91], v[74:75]
	v_cvt_pk_bf16_f32 v73, v80, v81
	v_cvt_pk_bf16_f32 v87, v74, v75
	v_mad_u32_u24 v5, v79, s21, v2
	ds_read_b64_tr_b16 v[82:83], v5 offset:38016
	ds_read_b64_tr_b16 v[80:81], v5 offset:36864
	ds_read_b64_tr_b16 v[88:89], v5 offset:36896
	s_waitcnt lgkmcnt(1)
	v_mfma_f32_16x16x32_bf16 v[22:25], v[70:73], v[80:83], v[22:25]
	ds_read_b64_tr_b16 v[90:91], v5 offset:38048
	v_mfma_f32_16x16x32_bf16 v[10:13], v[84:87], v[80:83], v[10:13]
	ds_read_b64_tr_b16 v[80:81], v5 offset:36928
	ds_read_b64_tr_b16 v[82:83], v5 offset:38080
	s_waitcnt lgkmcnt(0)
	v_mfma_f32_16x16x32_bf16 v[34:37], v[70:73], v[80:83], v[34:37]
	v_mfma_f32_16x16x32_bf16 v[30:33], v[84:87], v[80:83], v[30:33]
	ds_read_b64_tr_b16 v[80:81], v5 offset:36960
	ds_read_b64_tr_b16 v[82:83], v5 offset:38112
	s_waitcnt lgkmcnt(0)
	v_mfma_f32_16x16x32_bf16 v[42:45], v[70:73], v[80:83], v[42:45]
	v_mfma_f32_16x16x32_bf16 v[38:41], v[84:87], v[80:83], v[38:41]
	ds_read_b64_tr_b16 v[80:81], v5 offset:36992
	ds_read_b64_tr_b16 v[82:83], v5 offset:38144
	s_waitcnt lgkmcnt(0)
	v_mfma_f32_16x16x32_bf16 v[50:53], v[70:73], v[80:83], v[50:53]
	v_mfma_f32_16x16x32_bf16 v[46:49], v[84:87], v[80:83], v[46:49]
	ds_read_b64_tr_b16 v[80:81], v5 offset:37024
	ds_read_b64_tr_b16 v[82:83], v5 offset:38176
	s_waitcnt lgkmcnt(0)
	v_mfma_f32_16x16x32_bf16 v[58:61], v[70:73], v[80:83], v[58:61]
	v_mfma_f32_16x16x32_bf16 v[54:57], v[84:87], v[80:83], v[54:57]
	ds_read_b64_tr_b16 v[80:81], v5 offset:37056
	ds_read_b64_tr_b16 v[82:83], v5 offset:38208
	s_waitcnt lgkmcnt(0)
	v_mfma_f32_16x16x32_bf16 v[66:69], v[70:73], v[80:83], v[66:69]
	v_mfma_f32_16x16x32_bf16 v[62:65], v[84:87], v[80:83], v[62:65]
	ds_read_b64_tr_b16 v[80:81], v5 offset:37088
	ds_read_b64_tr_b16 v[82:83], v5 offset:38240
	v_or_b32_e32 v5, 0x60, v0
	v_or_b32_e32 v3, v5, v3
	v_mad_u32_u24 v4, v3, s21, v4
	v_lshlrev_b32_e32 v79, 2, v5
	v_mfma_f32_16x16x32_bf16 v[26:29], v[70:73], v[88:91], v[26:29]
	s_waitcnt lgkmcnt(0)
	v_mfma_f32_16x16x32_bf16 v[70:73], v[70:73], v[80:83], v[6:9]
	s_nop 2
	ds_read_b64_tr_b16 v[8:9], v4
	ds_read_b64_tr_b16 v[74:75], v4 offset:1152
	s_waitcnt lgkmcnt(1)
	v_lshlrev_b32_e32 v94, 16, v8
	v_mfma_f32_16x16x32_bf16 v[14:17], v[84:87], v[80:83], v[14:17]
	v_add_u32_e32 v80, s0, v79
	ds_read_b128 v[4:7], v80
	ds_read_b128 v[80:83], v80 offset:16
	v_add_u32_e32 v79, s28, v79
	v_mfma_f32_16x16x32_bf16 v[18:21], v[84:87], v[88:91], v[18:21]
	ds_read_b128 v[84:87], v79
	ds_read_b128 v[88:91], v79 offset:16
	v_and_b32_e32 v95, 0xffff0000, v8
	s_waitcnt lgkmcnt(3)
	v_pk_mul_f32 v[4:5], v[4:5], v[94:95]
	s_lshl_b32 s0, s50, 3
	v_cvt_pk_bf16_f32 v92, v4, v5
	s_waitcnt lgkmcnt(1)
	v_pk_mul_f32 v[4:5], v[84:85], v[94:95]
	s_or_b32 s5, s1, s0
	v_cvt_pk_bf16_f32 v84, v4, v5
	v_lshlrev_b32_e32 v4, 16, v9
	v_and_b32_e32 v5, 0xffff0000, v9
	v_pk_mul_f32 v[6:7], v[6:7], v[4:5]
	v_pk_mul_f32 v[4:5], v[86:87], v[4:5]
	v_cvt_pk_bf16_f32 v93, v6, v7
	v_cvt_pk_bf16_f32 v85, v4, v5
	v_lshlrev_b32_e32 v4, 16, v74
	v_and_b32_e32 v5, 0xffff0000, v74
	v_pk_mul_f32 v[6:7], v[80:81], v[4:5]
	s_waitcnt lgkmcnt(0)
	v_pk_mul_f32 v[4:5], v[88:89], v[4:5]
	v_cvt_pk_bf16_f32 v94, v6, v7
	v_cvt_pk_bf16_f32 v86, v4, v5
	v_lshlrev_b32_e32 v4, 16, v75
	v_and_b32_e32 v5, 0xffff0000, v75
	v_pk_mul_f32 v[6:7], v[82:83], v[4:5]
	v_pk_mul_f32 v[4:5], v[90:91], v[4:5]
	v_mad_u32_u24 v74, v3, s21, v2
	v_cvt_pk_bf16_f32 v87, v4, v5
	ds_read_b64_tr_b16 v[4:5], v74 offset:38016
	ds_read_b64_tr_b16 v[2:3], v74 offset:36864
	ds_read_b64_tr_b16 v[80:81], v74 offset:36896
	v_cvt_pk_bf16_f32 v95, v6, v7
	s_waitcnt lgkmcnt(1)
	v_mfma_f32_16x16x32_bf16 v[6:9], v[84:87], v[2:5], v[10:13]
	ds_read_b64_tr_b16 v[82:83], v74 offset:38048
	s_nop 1
	ds_read_b64_tr_b16 v[10:11], v74 offset:36928
	ds_read_b64_tr_b16 v[12:13], v74 offset:38080
	s_lshl_b32 s8, s5, 5
	v_mfma_f32_16x16x32_bf16 v[22:25], v[92:95], v[2:5], v[22:25]
	s_or_b32 s0, s8, s48
	s_ashr_i32 s1, s0, 31
	s_lshl_b64 s[0:1], s[0:1], 15
	s_waitcnt lgkmcnt(2)
	v_mfma_f32_16x16x32_bf16 v[2:5], v[84:87], v[80:83], v[18:21]
	s_add_u32 s0, s31, s0
	s_addc_u32 s1, s46, s1
	s_nop 0
	v_cvt_pk_bf16_f32 v22, v22, v23
	s_waitcnt lgkmcnt(0)
	v_mfma_f32_16x16x32_bf16 v[18:21], v[92:95], v[10:13], v[34:37]
	v_cvt_pk_bf16_f32 v23, v24, v25
	v_lshlrev_b32_e32 v24, 8, v78
	v_mov_b32_e32 v25, v1
	v_mfma_f32_16x16x32_bf16 v[10:13], v[84:87], v[10:13], v[30:33]
	s_nop 2
	ds_read_b64_tr_b16 v[30:31], v74 offset:36960
	ds_read_b64_tr_b16 v[32:33], v74 offset:38112
	v_cvt_pk_bf16_f32 v18, v18, v19
	v_cvt_pk_bf16_f32 v19, v20, v21
	s_waitcnt lgkmcnt(0)
	v_mfma_f32_16x16x32_bf16 v[34:37], v[92:95], v[30:33], v[42:45]
	v_or_b32_e32 v20, 0x2000, v24
	v_mov_b32_e32 v21, v1
	v_cvt_pk_bf16_f32 v2, v2, v3
	v_mfma_f32_16x16x32_bf16 v[30:33], v[84:87], v[30:33], v[38:41]
	s_nop 2
	ds_read_b64_tr_b16 v[38:39], v74 offset:36992
	ds_read_b64_tr_b16 v[40:41], v74 offset:38144
	v_cvt_pk_bf16_f32 v3, v4, v5
	v_cvt_pk_bf16_f32 v6, v6, v7
	s_waitcnt lgkmcnt(0)
	v_mfma_f32_16x16x32_bf16 v[42:45], v[92:95], v[38:41], v[50:53]
	v_cvt_pk_bf16_f32 v7, v8, v9
	v_mfma_f32_16x16x32_bf16 v[38:41], v[84:87], v[38:41], v[46:49]
	s_nop 2
	ds_read_b64_tr_b16 v[46:47], v74 offset:37024
	ds_read_b64_tr_b16 v[48:49], v74 offset:38176
	s_waitcnt lgkmcnt(0)
	v_mfma_f32_16x16x32_bf16 v[50:53], v[92:95], v[46:49], v[58:61]
	v_mfma_f32_16x16x32_bf16 v[46:49], v[84:87], v[46:49], v[54:57]
	s_nop 2
	ds_read_b64_tr_b16 v[54:55], v74 offset:37056
	ds_read_b64_tr_b16 v[56:57], v74 offset:38208
	s_waitcnt lgkmcnt(0)
	v_mfma_f32_16x16x32_bf16 v[58:61], v[92:95], v[54:57], v[66:69]
	v_mfma_f32_16x16x32_bf16 v[54:57], v[84:87], v[54:57], v[62:65]
	s_nop 2
	ds_read_b64_tr_b16 v[62:63], v74 offset:37088
	ds_read_b64_tr_b16 v[64:65], v74 offset:38240
	s_waitcnt lgkmcnt(0)
	v_mfma_f32_16x16x32_bf16 v[66:69], v[92:95], v[62:65], v[70:73]
	v_mfma_f32_16x16x32_bf16 v[14:17], v[84:87], v[62:65], v[14:17]
	v_lshlrev_b32_e32 v62, 4, v77
	v_ashrrev_i32_e32 v63, 31, v62
	v_lshlrev_b64 v[62:63], 1, v[62:63]
	v_mfma_f32_16x16x32_bf16 v[26:29], v[92:95], v[80:83], v[26:29]
	v_lshl_add_u64 v[64:65], s[0:1], 0, v[62:63]
	v_lshl_add_u64 v[64:65], v[64:65], 0, v[0:1]
	v_lshl_add_u64 v[70:71], v[64:65], 0, v[24:25]
	global_store_dwordx2 v[70:71], v[22:23], off
	s_or_b32 s0, s4, s8
	s_nop 2
	v_cvt_pk_bf16_f32 v22, v26, v27
	v_or_b32_e32 v26, 0x1000, v24
	v_mov_b32_e32 v27, v1
	v_cvt_pk_bf16_f32 v23, v28, v29
	v_lshl_add_u64 v[28:29], v[64:65], 0, v[26:27]
	global_store_dwordx2 v[28:29], v[22:23], off
	v_lshl_add_u64 v[22:23], v[64:65], 0, v[20:21]
	global_store_dwordx2 v[22:23], v[18:19], off
	v_or_b32_e32 v22, 0x3000, v24
	v_mov_b32_e32 v23, v1
	v_cvt_pk_bf16_f32 v18, v34, v35
	v_cvt_pk_bf16_f32 v19, v36, v37
	v_lshl_add_u64 v[28:29], v[64:65], 0, v[22:23]
	global_store_dwordx2 v[28:29], v[18:19], off
	v_or_b32_e32 v28, 0x4000, v24
	v_mov_b32_e32 v29, v1
	v_cvt_pk_bf16_f32 v18, v42, v43
	v_cvt_pk_bf16_f32 v19, v44, v45
	v_lshl_add_u64 v[34:35], v[64:65], 0, v[28:29]
	global_store_dwordx2 v[34:35], v[18:19], off
	v_or_b32_e32 v34, 0x5000, v24
	v_mov_b32_e32 v35, v1
	v_cvt_pk_bf16_f32 v18, v50, v51
	v_cvt_pk_bf16_f32 v19, v52, v53
	v_lshl_add_u64 v[36:37], v[64:65], 0, v[34:35]
	s_or_b32 s0, s0, 32
	global_store_dwordx2 v[36:37], v[18:19], off
	v_or_b32_e32 v36, 0x6000, v24
	v_mov_b32_e32 v37, v1
	s_ashr_i32 s1, s0, 31
	v_cvt_pk_bf16_f32 v18, v58, v59
	v_cvt_pk_bf16_f32 v19, v60, v61
	v_lshl_add_u64 v[42:43], v[64:65], 0, v[36:37]
	s_lshl_b64 s[0:1], s[0:1], 15
	global_store_dwordx2 v[42:43], v[18:19], off
	v_or_b32_e32 v42, 0x7000, v24
	v_mov_b32_e32 v43, v1
	s_add_u32 s0, s31, s0
	v_cvt_pk_bf16_f32 v18, v66, v67
	v_cvt_pk_bf16_f32 v19, v68, v69
	v_lshl_add_u64 v[44:45], v[64:65], 0, v[42:43]
	s_addc_u32 s1, s46, s1
	global_store_dwordx2 v[44:45], v[18:19], off
	v_lshl_add_u64 v[18:19], s[0:1], 0, v[62:63]
	v_lshl_add_u64 v[18:19], v[18:19], 0, v[0:1]
	v_lshl_add_u64 v[4:5], v[18:19], 0, v[26:27]
	global_store_dwordx2 v[4:5], v[2:3], off
	v_cvt_pk_bf16_f32 v2, v10, v11
	v_cvt_pk_bf16_f32 v3, v12, v13
	v_lshl_add_u64 v[4:5], v[18:19], 0, v[20:21]
	global_store_dwordx2 v[4:5], v[2:3], off
	v_cvt_pk_bf16_f32 v2, v30, v31
	v_cvt_pk_bf16_f32 v3, v32, v33
	v_lshl_add_u64 v[4:5], v[18:19], 0, v[22:23]
	global_store_dwordx2 v[4:5], v[2:3], off
	v_cvt_pk_bf16_f32 v2, v38, v39
	v_cvt_pk_bf16_f32 v3, v40, v41
	v_lshl_add_u64 v[4:5], v[18:19], 0, v[28:29]
	global_store_dwordx2 v[4:5], v[2:3], off
	v_cvt_pk_bf16_f32 v2, v46, v47
	v_cvt_pk_bf16_f32 v3, v48, v49
	v_lshl_add_u64 v[4:5], v[18:19], 0, v[34:35]
	global_store_dwordx2 v[4:5], v[2:3], off
	v_cvt_pk_bf16_f32 v2, v54, v55
	v_cvt_pk_bf16_f32 v3, v56, v57
	v_lshl_add_u64 v[4:5], v[18:19], 0, v[36:37]
	s_movk_i32 s0, 0x100
	v_lshl_add_u64 v[8:9], v[18:19], 0, v[24:25]
	global_store_dwordx2 v[4:5], v[2:3], off
	v_cvt_pk_bf16_f32 v2, v14, v15
	v_cvt_pk_bf16_f32 v3, v16, v17
	v_lshl_add_u64 v[4:5], v[18:19], 0, v[42:43]
	v_cmp_gt_i32_e32 vcc, s0, v76
	global_store_dwordx2 v[8:9], v[6:7], off
	global_store_dwordx2 v[4:5], v[2:3], off
	s_and_saveexec_b64 s[0:1], vcc
	s_cbranch_execz .LBB0_360
	v_lshlrev_b32_e32 v2, 2, v76
	v_and_b32_e32 v0, 0x7f, v76
	v_and_b32_e32 v2, 0xfffffe00, v2
	v_lshl_add_u32 v3, v0, 1, 0
	v_add_u32_e32 v4, 0, v2
	v_mov_b32_e32 v2, 0
	s_mov_b32 s8, 0

.LBB0_747:
	s_or_b64 exec, exec, s[0:1]
	s_lshl_b32 s87, s8, 2
	s_add_u32 s0, s30, s87
	s_addc_u32 s1, s31, 0
	v_lshlrev_b32_e32 v0, 2, v77
	v_lshl_add_u64 v[22:23], s[0:1], 0, v[0:1]
	v_add_co_u32_e32 v24, vcc, s64, v22
	v_lshl_add_u64 v[18:19], v[22:23], 0, s[88:89]
	s_nop 0
	v_addc_co_u32_e32 v25, vcc, 0, v23, vcc
	global_load_dwordx4 v[14:17], v0, s[0:1] offset:16
	global_load_dwordx4 v[30:33], v0, s[0:1]
	s_waitcnt lgkmcnt(0)
	global_load_dwordx4 v[38:41], v[24:25], off offset:-4096
	s_nop 0
	global_load_dwordx4 v[18:21], v[18:19], off offset:16
	s_mov_b64 s[4:5], 0x2000
	v_lshl_add_u64 v[22:23], v[22:23], 0, s[4:5]
	global_load_dwordx4 v[46:49], v[24:25], off
	s_nop 0
	global_load_dwordx4 v[22:25], v[22:23], off offset:16
	s_waitcnt vmcnt(9)
	v_lshlrev_b32_e32 v80, 16, v70
	v_and_b32_e32 v81, 0xffff0000, v70
	v_lshlrev_b32_e32 v78, 16, v66
	v_and_b32_e32 v79, 0xffff0000, v66
	v_lshlrev_b32_e32 v70, 16, v71
	v_and_b32_e32 v71, 0xffff0000, v71
	v_lshlrev_b32_e32 v66, 16, v67
	v_and_b32_e32 v67, 0xffff0000, v67
	v_lshlrev_b32_e32 v0, 1, v77
	s_waitcnt vmcnt(3)
	v_pk_mul_f32 v[80:81], v[38:39], v[80:81]
	s_nop 0
	v_pk_fma_f32 v[78:79], v[30:31], v[78:79], v[80:81]
	v_lshlrev_b32_e32 v80, 16, v62
	v_and_b32_e32 v81, 0xffff0000, v62
	s_waitcnt vmcnt(1)
	v_pk_fma_f32 v[78:79], v[46:47], v[80:81], v[78:79]
	v_pk_mul_f32 v[70:71], v[40:41], v[70:71]
	v_mul_f32_e32 v62, 0xbfb8aa3b, v78
	v_exp_f32_e32 v62, v62
	v_pk_fma_f32 v[66:67], v[32:33], v[66:67], v[70:71]
	v_lshlrev_b32_e32 v70, 16, v72
	v_and_b32_e32 v71, 0xffff0000, v72
	v_add_f32_e32 v62, 1.0, v62
	v_rcp_f32_e32 v80, v62
	v_mul_f32_e32 v62, 0xbfb8aa3b, v79
	v_exp_f32_e32 v62, v62
	v_pk_mul_f32 v[70:71], v[18:19], v[70:71]
	v_add_f32_e32 v62, 1.0, v62
	v_rcp_f32_e32 v81, v62
	v_lshlrev_b32_e32 v62, 16, v63
	v_and_b32_e32 v63, 0xffff0000, v63
	v_pk_fma_f32 v[62:63], v[48:49], v[62:63], v[66:67]
	v_pk_mul_f32 v[78:79], v[78:79], v[80:81]
	v_mul_f32_e32 v66, 0xbfb8aa3b, v62
	v_mul_f32_e32 v67, 0xbfb8aa3b, v63
	v_exp_f32_e32 v66, v66
	v_exp_f32_e32 v67, v67
	v_add_f32_e32 v66, 1.0, v66
	v_add_f32_e32 v67, 1.0, v67
	v_rcp_f32_e32 v66, v66
	v_rcp_f32_e32 v67, v67
	s_nop 0
	v_pk_mul_f32 v[66:67], v[62:63], v[66:67]
	v_lshlrev_b32_e32 v62, 16, v68
	v_and_b32_e32 v63, 0xffff0000, v68
	v_pk_fma_f32 v[62:63], v[14:15], v[62:63], v[70:71]
	v_lshlrev_b32_e32 v70, 16, v64
	v_and_b32_e32 v71, 0xffff0000, v64
	s_waitcnt vmcnt(0)
	v_pk_fma_f32 v[62:63], v[22:23], v[70:71], v[62:63]
	v_lshlrev_b32_e32 v68, 16, v73
	v_mul_f32_e32 v64, 0xbfb8aa3b, v62
	v_exp_f32_e32 v64, v64
	s_nop 0
	v_add_f32_e32 v64, 1.0, v64
	v_rcp_f32_e32 v70, v64
	v_mul_f32_e32 v64, 0xbfb8aa3b, v63
	v_exp_f32_e32 v64, v64
	s_nop 0
	v_add_f32_e32 v64, 1.0, v64
	v_rcp_f32_e32 v71, v64
	v_lshlrev_b32_e32 v64, 16, v65
	v_and_b32_e32 v65, 0xffff0000, v65
	v_pk_mul_f32 v[70:71], v[62:63], v[70:71]
	v_lshlrev_b32_e32 v62, 16, v69
	v_and_b32_e32 v63, 0xffff0000, v69
	v_and_b32_e32 v69, 0xffff0000, v73
	v_pk_mul_f32 v[68:69], v[20:21], v[68:69]
	s_nop 0
	v_pk_fma_f32 v[62:63], v[16:17], v[62:63], v[68:69]
	s_nop 0
	v_pk_fma_f32 v[62:63], v[24:25], v[64:65], v[62:63]
	s_nop 0
	v_mul_f32_e32 v64, 0xbfb8aa3b, v62
	v_mul_f32_e32 v65, 0xbfb8aa3b, v63
	v_exp_f32_e32 v64, v64
	v_exp_f32_e32 v65, v65
	v_add_f32_e32 v64, 1.0, v64
	v_add_f32_e32 v65, 1.0, v65
	v_rcp_f32_e32 v64, v64
	v_rcp_f32_e32 v65, v65
	s_nop 0
	v_pk_mul_f32 v[68:69], v[62:63], v[64:65]
	v_cvt_pk_bf16_f32 v63, v66, v67
	v_mul_lo_u32 v66, v75, s21
	v_cvt_pk_bf16_f32 v62, v78, v79
	v_cvt_pk_bf16_f32 v64, v70, v71
	v_cvt_pk_bf16_f32 v65, v68, v69
	v_add3_u32 v0, 0, v0, v66
	ds_write_b128 v0, v[62:65]
	v_lshlrev_b32_e32 v64, 16, v58
	v_and_b32_e32 v65, 0xffff0000, v58
	v_lshlrev_b32_e32 v62, 16, v54
	v_and_b32_e32 v63, 0xffff0000, v54
	v_pk_mul_f32 v[64:65], v[38:39], v[64:65]
	v_lshlrev_b32_e32 v58, 16, v59
	v_pk_fma_f32 v[62:63], v[30:31], v[62:63], v[64:65]
	v_lshlrev_b32_e32 v64, 16, v50
	v_and_b32_e32 v65, 0xffff0000, v50
	v_pk_fma_f32 v[62:63], v[46:47], v[64:65], v[62:63]
	v_and_b32_e32 v59, 0xffff0000, v59
	v_mul_f32_e32 v50, 0xbfb8aa3b, v62
	v_exp_f32_e32 v50, v50
	v_lshlrev_b32_e32 v54, 16, v55
	v_and_b32_e32 v55, 0xffff0000, v55
	v_pk_mul_f32 v[58:59], v[40:41], v[58:59]
	v_add_f32_e32 v50, 1.0, v50
	v_rcp_f32_e32 v64, v50
	v_mul_f32_e32 v50, 0xbfb8aa3b, v63
	v_exp_f32_e32 v50, v50
	v_pk_fma_f32 v[54:55], v[32:33], v[54:55], v[58:59]
	v_lshlrev_b32_e32 v58, 16, v60
	v_and_b32_e32 v59, 0xffff0000, v60
	v_add_f32_e32 v50, 1.0, v50
	v_rcp_f32_e32 v65, v50
	v_lshlrev_b32_e32 v50, 16, v51
	v_and_b32_e32 v51, 0xffff0000, v51
	v_pk_fma_f32 v[50:51], v[48:49], v[50:51], v[54:55]
	v_pk_mul_f32 v[58:59], v[18:19], v[58:59]
	v_mul_f32_e32 v54, 0xbfb8aa3b, v50
	v_mul_f32_e32 v55, 0xbfb8aa3b, v51
	v_exp_f32_e32 v54, v54
	v_exp_f32_e32 v55, v55
	v_pk_mul_f32 v[62:63], v[62:63], v[64:65]
	v_mov_b32_e32 v66, 0
	v_add_f32_e32 v54, 1.0, v54
	v_add_f32_e32 v55, 1.0, v55
	v_rcp_f32_e32 v54, v54
	v_rcp_f32_e32 v55, v55
	v_mov_b32_e32 v67, 0
	v_mov_b32_e32 v68, 0
	v_mov_b32_e32 v69, 0
	v_pk_mul_f32 v[54:55], v[50:51], v[54:55]
	v_lshlrev_b32_e32 v50, 16, v56
	v_and_b32_e32 v51, 0xffff0000, v56
	v_pk_fma_f32 v[50:51], v[14:15], v[50:51], v[58:59]
	v_lshlrev_b32_e32 v58, 16, v52
	v_and_b32_e32 v59, 0xffff0000, v52
	v_pk_fma_f32 v[50:51], v[22:23], v[58:59], v[50:51]
	v_lshlrev_b32_e32 v56, 16, v61
	v_mul_f32_e32 v52, 0xbfb8aa3b, v50
	v_exp_f32_e32 v52, v52
	s_nop 0
	v_add_f32_e32 v52, 1.0, v52
	v_rcp_f32_e32 v58, v52
	v_mul_f32_e32 v52, 0xbfb8aa3b, v51
	v_exp_f32_e32 v52, v52
	s_nop 0
	v_add_f32_e32 v52, 1.0, v52
	v_rcp_f32_e32 v59, v52
	v_lshlrev_b32_e32 v52, 16, v53
	v_and_b32_e32 v53, 0xffff0000, v53
	v_pk_mul_f32 v[58:59], v[50:51], v[58:59]
	v_lshlrev_b32_e32 v50, 16, v57
	v_and_b32_e32 v51, 0xffff0000, v57
	v_and_b32_e32 v57, 0xffff0000, v61
	v_pk_mul_f32 v[56:57], v[20:21], v[56:57]
	s_nop 0
	v_pk_fma_f32 v[50:51], v[16:17], v[50:51], v[56:57]
	s_nop 0
	v_pk_fma_f32 v[50:51], v[24:25], v[52:53], v[50:51]
	s_nop 0
	v_mul_f32_e32 v52, 0xbfb8aa3b, v50
	v_mul_f32_e32 v53, 0xbfb8aa3b, v51
	v_exp_f32_e32 v52, v52
	v_exp_f32_e32 v53, v53
	v_add_f32_e32 v52, 1.0, v52
	v_add_f32_e32 v53, 1.0, v53
	v_rcp_f32_e32 v52, v52
	v_rcp_f32_e32 v53, v53
	s_nop 0
	v_pk_mul_f32 v[56:57], v[50:51], v[52:53]
	v_cvt_pk_bf16_f32 v50, v62, v63
	v_cvt_pk_bf16_f32 v51, v54, v55
	v_cvt_pk_bf16_f32 v52, v58, v59
	v_cvt_pk_bf16_f32 v53, v56, v57
	ds_write_b128 v0, v[50:53] offset:9216
	v_lshlrev_b32_e32 v52, 16, v42
	v_and_b32_e32 v53, 0xffff0000, v42
	v_lshlrev_b32_e32 v50, 16, v34
	v_and_b32_e32 v51, 0xffff0000, v34
	v_pk_mul_f32 v[52:53], v[38:39], v[52:53]
	v_lshlrev_b32_e32 v42, 16, v43
	v_pk_fma_f32 v[50:51], v[30:31], v[50:51], v[52:53]
	v_lshlrev_b32_e32 v52, 16, v26
	v_and_b32_e32 v53, 0xffff0000, v26
	v_pk_fma_f32 v[50:51], v[46:47], v[52:53], v[50:51]
	v_and_b32_e32 v43, 0xffff0000, v43
	v_mul_f32_e32 v26, 0xbfb8aa3b, v50
	v_exp_f32_e32 v26, v26
	v_lshlrev_b32_e32 v34, 16, v35
	v_and_b32_e32 v35, 0xffff0000, v35
	v_pk_mul_f32 v[42:43], v[40:41], v[42:43]
	v_add_f32_e32 v26, 1.0, v26
	v_rcp_f32_e32 v52, v26
	v_mul_f32_e32 v26, 0xbfb8aa3b, v51
	v_exp_f32_e32 v26, v26
	v_pk_fma_f32 v[34:35], v[32:33], v[34:35], v[42:43]
	v_lshlrev_b32_e32 v42, 16, v44
	v_and_b32_e32 v43, 0xffff0000, v44
	v_add_f32_e32 v26, 1.0, v26
	v_rcp_f32_e32 v53, v26
	v_lshlrev_b32_e32 v26, 16, v27
	v_and_b32_e32 v27, 0xffff0000, v27
	v_pk_fma_f32 v[26:27], v[48:49], v[26:27], v[34:35]
	v_pk_mul_f32 v[42:43], v[18:19], v[42:43]
	v_mul_f32_e32 v34, 0xbfb8aa3b, v26
	v_mul_f32_e32 v35, 0xbfb8aa3b, v27
	v_exp_f32_e32 v34, v34
	v_exp_f32_e32 v35, v35
	v_pk_mul_f32 v[50:51], v[50:51], v[52:53]
	v_mov_b32_e32 v62, 0
	v_add_f32_e32 v34, 1.0, v34
	v_add_f32_e32 v35, 1.0, v35
	v_rcp_f32_e32 v34, v34
	v_rcp_f32_e32 v35, v35
	s_nop 0
	v_pk_mul_f32 v[34:35], v[26:27], v[34:35]
	v_lshlrev_b32_e32 v26, 16, v36
	v_and_b32_e32 v27, 0xffff0000, v36
	v_pk_fma_f32 v[26:27], v[14:15], v[26:27], v[42:43]
	v_lshlrev_b32_e32 v42, 16, v28
	v_and_b32_e32 v43, 0xffff0000, v28
	v_pk_fma_f32 v[26:27], v[22:23], v[42:43], v[26:27]
	v_lshlrev_b32_e32 v36, 16, v45
	v_mul_f32_e32 v28, 0xbfb8aa3b, v26
	v_exp_f32_e32 v28, v28
	s_nop 0
	v_add_f32_e32 v28, 1.0, v28
	v_rcp_f32_e32 v42, v28
	v_mul_f32_e32 v28, 0xbfb8aa3b, v27
	v_exp_f32_e32 v28, v28
	s_nop 0
	v_add_f32_e32 v28, 1.0, v28
	v_rcp_f32_e32 v43, v28
	v_lshlrev_b32_e32 v28, 16, v29
	v_and_b32_e32 v29, 0xffff0000, v29
	v_pk_mul_f32 v[42:43], v[26:27], v[42:43]
	v_lshlrev_b32_e32 v26, 16, v37
	v_and_b32_e32 v27, 0xffff0000, v37
	v_and_b32_e32 v37, 0xffff0000, v45
	v_pk_mul_f32 v[36:37], v[20:21], v[36:37]
	s_nop 0
	v_pk_fma_f32 v[26:27], v[16:17], v[26:27], v[36:37]
	s_nop 0
	v_pk_fma_f32 v[26:27], v[24:25], v[28:29], v[26:27]
	s_nop 0
	v_mul_f32_e32 v28, 0xbfb8aa3b, v26
	v_mul_f32_e32 v29, 0xbfb8aa3b, v27
	v_exp_f32_e32 v28, v28
	v_exp_f32_e32 v29, v29
	v_add_f32_e32 v28, 1.0, v28
	v_add_f32_e32 v29, 1.0, v29
	v_rcp_f32_e32 v28, v28
	v_rcp_f32_e32 v29, v29
	s_nop 0
	v_pk_mul_f32 v[36:37], v[26:27], v[28:29]
	v_cvt_pk_bf16_f32 v26, v50, v51
	v_cvt_pk_bf16_f32 v27, v34, v35
	v_cvt_pk_bf16_f32 v28, v42, v43
	v_cvt_pk_bf16_f32 v29, v36, v37
	ds_write_b128 v0, v[26:29] offset:18432
	v_lshlrev_b32_e32 v28, 16, v10
	v_and_b32_e32 v29, 0xffff0000, v10
	v_lshlrev_b32_e32 v26, 16, v6
	v_and_b32_e32 v27, 0xffff0000, v6
	v_pk_mul_f32 v[28:29], v[38:39], v[28:29]
	v_lshlrev_b32_e32 v10, 16, v11
	v_pk_fma_f32 v[26:27], v[30:31], v[26:27], v[28:29]
	v_lshlrev_b32_e32 v28, 16, v2
	v_and_b32_e32 v29, 0xffff0000, v2
	v_pk_fma_f32 v[26:27], v[46:47], v[28:29], v[26:27]
	v_and_b32_e32 v11, 0xffff0000, v11
	v_mul_f32_e32 v2, 0xbfb8aa3b, v26
	v_exp_f32_e32 v2, v2
	v_lshlrev_b32_e32 v6, 16, v7
	v_and_b32_e32 v7, 0xffff0000, v7
	v_pk_mul_f32 v[10:11], v[40:41], v[10:11]
	v_add_f32_e32 v2, 1.0, v2
	v_rcp_f32_e32 v28, v2
	v_mul_f32_e32 v2, 0xbfb8aa3b, v27
	v_exp_f32_e32 v2, v2
	v_pk_fma_f32 v[6:7], v[32:33], v[6:7], v[10:11]
	v_lshlrev_b32_e32 v10, 16, v12
	v_and_b32_e32 v11, 0xffff0000, v12
	v_add_f32_e32 v2, 1.0, v2
	v_rcp_f32_e32 v29, v2
	v_lshlrev_b32_e32 v2, 16, v3
	v_and_b32_e32 v3, 0xffff0000, v3
	v_pk_fma_f32 v[2:3], v[48:49], v[2:3], v[6:7]
	v_pk_mul_f32 v[10:11], v[18:19], v[10:11]
	v_mul_f32_e32 v6, 0xbfb8aa3b, v2
	v_mul_f32_e32 v7, 0xbfb8aa3b, v3
	v_exp_f32_e32 v6, v6
	v_exp_f32_e32 v7, v7
	v_pk_mul_f32 v[26:27], v[26:27], v[28:29]
	v_add_f32_e32 v6, 1.0, v6
	v_add_f32_e32 v7, 1.0, v7
	v_rcp_f32_e32 v6, v6
	v_rcp_f32_e32 v7, v7
	s_nop 0
	v_pk_mul_f32 v[6:7], v[2:3], v[6:7]
	v_lshlrev_b32_e32 v2, 16, v8
	v_and_b32_e32 v3, 0xffff0000, v8
	v_pk_fma_f32 v[2:3], v[14:15], v[2:3], v[10:11]
	v_lshlrev_b32_e32 v10, 16, v4
	v_and_b32_e32 v11, 0xffff0000, v4
	v_pk_fma_f32 v[2:3], v[22:23], v[10:11], v[2:3]
	v_lshlrev_b32_e32 v8, 16, v13
	v_mul_f32_e32 v4, 0xbfb8aa3b, v2
	v_exp_f32_e32 v4, v4
	s_nop 0
	v_add_f32_e32 v4, 1.0, v4
	v_rcp_f32_e32 v10, v4
	v_mul_f32_e32 v4, 0xbfb8aa3b, v3
	v_exp_f32_e32 v4, v4
	s_nop 0
	v_add_f32_e32 v4, 1.0, v4
	v_rcp_f32_e32 v11, v4
	v_lshlrev_b32_e32 v4, 16, v5
	v_and_b32_e32 v5, 0xffff0000, v5
	v_pk_mul_f32 v[10:11], v[2:3], v[10:11]
	v_lshlrev_b32_e32 v2, 16, v9
	v_and_b32_e32 v3, 0xffff0000, v9
	v_and_b32_e32 v9, 0xffff0000, v13
	v_pk_mul_f32 v[8:9], v[20:21], v[8:9]
	s_nop 0
	v_pk_fma_f32 v[2:3], v[16:17], v[2:3], v[8:9]
	s_nop 0
	v_pk_fma_f32 v[2:3], v[24:25], v[4:5], v[2:3]
	s_nop 0
	v_mul_f32_e32 v4, 0xbfb8aa3b, v2
	v_mul_f32_e32 v5, 0xbfb8aa3b, v3
	v_exp_f32_e32 v4, v4
	v_exp_f32_e32 v5, v5
	v_add_f32_e32 v4, 1.0, v4
	v_add_f32_e32 v5, 1.0, v5
	v_rcp_f32_e32 v4, v4
	v_rcp_f32_e32 v5, v5
	s_nop 0
	v_pk_mul_f32 v[8:9], v[2:3], v[4:5]
	v_cvt_pk_bf16_f32 v2, v26, v27
	v_cvt_pk_bf16_f32 v3, v6, v7
	v_cvt_pk_bf16_f32 v4, v10, v11
	v_cvt_pk_bf16_f32 v5, v8, v9
	ds_write_b128 v0, v[2:5] offset:27648
	v_lshrrev_b32_e32 v100, 4, v192
	v_add_u32_e32 v100, s86, v100
	v_mov_b64_e32 v[120:121], s[50:51]
	s_lshl_b32 s44, s78, 8
	s_mov_b32 s45, s9
	v_lshlrev_b32_e32 v102, 4, v192
	v_and_b32_e32 v102, 0xf0, v102
	v_mov_b32_e32 v103, 0
	v_mad_i64_i32 v[122:123], s[12:13], v100, s65, v[120:121]
	v_lshl_add_u64 v[122:123], v[122:123], 0, s[44:45]
	v_lshl_add_u64 v[122:123], v[122:123], 0, v[102:103]
	global_load_dwordx4 v[104:107], v[122:123], off offset:2048
	v_add_u32_e32 v101, 32, v100
	v_mad_i64_i32 v[122:123], s[12:13], v101, s65, v[120:121]
	v_lshl_add_u64 v[122:123], v[122:123], 0, s[44:45]
	v_lshl_add_u64 v[122:123], v[122:123], 0, v[102:103]
	global_load_dwordx4 v[108:111], v[122:123], off offset:2048
	v_add_u32_e32 v101, 64, v100
	v_mad_i64_i32 v[122:123], s[12:13], v101, s65, v[120:121]
	v_lshl_add_u64 v[122:123], v[122:123], 0, s[44:45]
	v_lshl_add_u64 v[122:123], v[122:123], 0, v[102:103]
	global_load_dwordx4 v[112:115], v[122:123], off offset:2048
	v_add_u32_e32 v101, 96, v100
	v_mad_i64_i32 v[122:123], s[12:13], v101, s65, v[120:121]
	v_lshl_add_u64 v[122:123], v[122:123], 0, s[44:45]
	v_lshl_add_u64 v[122:123], v[122:123], 0, v[102:103]
	global_load_dwordx4 v[116:119], v[122:123], off offset:2048
	v_mov_b32_e32 v0, v192
	s_nop 0
	v_ashrrev_i32_e32 v77, 4, v0
	v_lshlrev_b32_e32 v0, 3, v0
	v_and_b32_e32 v75, 0x78, v0
	v_or_b32_e32 v0, s8, v75
	v_add_u32_e32 v16, s86, v77
	v_lshlrev_b32_e32 v0, 1, v0
	v_lshl_add_u64 v[14:15], s[50:51], 0, v[0:1]
	v_cmp_lt_i32_e32 vcc, 0, v16
	s_and_saveexec_b64 s[4:5], vcc
	s_cbranch_execz .LBB0_749
	v_add_u32_e32 v0, -1, v16
	v_mad_u64_u32 v[2:3], s[18:19], v0, s65, v[14:15]
	global_load_dwordx4 v[66:69], v[2:3], off offset:1024

.LBB0_763:
	s_or_b64 exec, exec, s[4:5]
	v_lshlrev_b32_e32 v0, 2, v75
	v_lshl_add_u64 v[22:23], s[0:1], 0, v[0:1]
	global_load_dwordx4 v[14:17], v0, s[0:1] offset:2064
	global_load_dwordx4 v[26:29], v0, s[0:1] offset:2048
	s_mov_b64 s[0:1], 0x1800
	v_add_co_u32_e32 v20, vcc, 0x1000, v22
	v_lshl_add_u64 v[18:19], v[22:23], 0, s[0:1]
	s_nop 0
	v_addc_co_u32_e32 v21, vcc, 0, v23, vcc
	s_mov_b64 s[0:1], 0x2800
	global_load_dwordx4 v[30:33], v[20:21], off offset:2048
	s_nop 0
	global_load_dwordx4 v[18:21], v[18:19], off offset:16
	v_lshl_add_u64 v[24:25], v[22:23], 0, s[0:1]
	v_add_co_u32_e32 v22, vcc, s64, v22
	s_waitcnt vmcnt(7)
	v_lshlrev_b32_e32 v78, 16, v70
	v_addc_co_u32_e32 v23, vcc, 0, v23, vcc
	global_load_dwordx4 v[42:45], v[22:23], off offset:2048
	s_nop 0
	global_load_dwordx4 v[22:25], v[24:25], off offset:16
	v_and_b32_e32 v79, 0xffff0000, v70
	v_lshrrev_b32_e32 v88, 4, v74
	v_lshlrev_b32_e32 v0, 1, v75
	v_lshlrev_b32_e32 v74, 16, v66
	v_and_b32_e32 v75, 0xffff0000, v66
	v_lshlrev_b32_e32 v70, 16, v71
	v_and_b32_e32 v71, 0xffff0000, v71
	v_lshlrev_b32_e32 v66, 16, v67
	v_and_b32_e32 v67, 0xffff0000, v67
	s_lshl_b32 s8, s8, 1
	s_add_i32 s68, 0, 0x12000
	v_and_b32_e32 v94, 15, v76
	v_lshlrev_b32_e32 v96, 4, v86
	v_lshlrev_b32_e32 v95, 2, v88
	s_waitcnt vmcnt(3)
	v_pk_mul_f32 v[78:79], v[30:31], v[78:79]
	s_nop 0
	v_pk_fma_f32 v[74:75], v[26:27], v[74:75], v[78:79]
	v_lshlrev_b32_e32 v78, 16, v62
	v_and_b32_e32 v79, 0xffff0000, v62
	v_pk_mul_f32 v[70:71], v[32:33], v[70:71]
	s_waitcnt vmcnt(1)
	v_pk_fma_f32 v[74:75], v[42:43], v[78:79], v[74:75]
	s_nop 0
	v_mul_f32_e32 v62, 0xbfb8aa3b, v74
	v_exp_f32_e32 v62, v62
	v_pk_fma_f32 v[66:67], v[28:29], v[66:67], v[70:71]
	v_lshlrev_b32_e32 v70, 16, v72
	v_and_b32_e32 v71, 0xffff0000, v72
	v_add_f32_e32 v62, 1.0, v62
	v_rcp_f32_e32 v78, v62
	v_mul_f32_e32 v62, 0xbfb8aa3b, v75
	v_exp_f32_e32 v62, v62
	v_pk_mul_f32 v[70:71], v[18:19], v[70:71]
	v_mov_b32_e32 v72, 0
	v_add_f32_e32 v62, 1.0, v62
	v_rcp_f32_e32 v79, v62
	v_lshlrev_b32_e32 v62, 16, v63
	v_and_b32_e32 v63, 0xffff0000, v63
	v_pk_fma_f32 v[62:63], v[44:45], v[62:63], v[66:67]
	v_pk_mul_f32 v[74:75], v[74:75], v[78:79]
	v_mul_f32_e32 v66, 0xbfb8aa3b, v62
	v_mul_f32_e32 v67, 0xbfb8aa3b, v63
	v_exp_f32_e32 v66, v66
	v_exp_f32_e32 v67, v67
	v_pk_mul_f32 v[74:75], v[74:75], s[22:23] op_sel_hi:[1,0]
	v_add_f32_e32 v66, 1.0, v66
	v_add_f32_e32 v67, 1.0, v67
	v_rcp_f32_e32 v66, v66
	v_rcp_f32_e32 v67, v67
	s_nop 0
	v_pk_mul_f32 v[62:63], v[62:63], v[66:67]
	v_lshlrev_b32_e32 v66, 16, v68
	v_and_b32_e32 v67, 0xffff0000, v68
	v_pk_fma_f32 v[66:67], v[14:15], v[66:67], v[70:71]
	v_lshlrev_b32_e32 v70, 16, v64
	v_and_b32_e32 v71, 0xffff0000, v64
	s_waitcnt vmcnt(0)
	v_pk_fma_f32 v[66:67], v[22:23], v[70:71], v[66:67]
	v_lshlrev_b32_e32 v68, 16, v69
	v_mul_f32_e32 v64, 0xbfb8aa3b, v66
	v_exp_f32_e32 v64, v64
	v_and_b32_e32 v69, 0xffff0000, v69
	v_pk_mul_f32 v[62:63], v[62:63], s[22:23] op_sel_hi:[1,0]
	v_add_f32_e32 v64, 1.0, v64
	v_rcp_f32_e32 v70, v64
	v_mul_f32_e32 v64, 0xbfb8aa3b, v67
	v_exp_f32_e32 v64, v64
	s_nop 0
	v_add_f32_e32 v64, 1.0, v64
	v_rcp_f32_e32 v71, v64
	v_lshlrev_b32_e32 v64, 16, v65
	v_and_b32_e32 v65, 0xffff0000, v65
	v_pk_mul_f32 v[66:67], v[66:67], v[70:71]
	v_lshlrev_b32_e32 v70, 16, v73
	v_and_b32_e32 v71, 0xffff0000, v73
	v_pk_mul_f32 v[70:71], v[20:21], v[70:71]
	v_pk_mul_f32 v[66:67], v[66:67], s[22:23] op_sel_hi:[1,0]
	v_pk_fma_f32 v[68:69], v[16:17], v[68:69], v[70:71]
	v_cvt_pk_bf16_f32 v66, v66, v67
	v_pk_fma_f32 v[64:65], v[24:25], v[64:65], v[68:69]
	v_mov_b32_e32 v73, 0
	v_mul_f32_e32 v68, 0xbfb8aa3b, v64
	v_mul_f32_e32 v69, 0xbfb8aa3b, v65
	v_exp_f32_e32 v68, v68
	v_exp_f32_e32 v69, v69
	v_add_f32_e32 v68, 1.0, v68
	v_add_f32_e32 v69, 1.0, v69
	v_rcp_f32_e32 v68, v68
	v_rcp_f32_e32 v69, v69
	s_nop 0
	v_pk_mul_f32 v[64:65], v[64:65], v[68:69]
	s_nop 0
	v_pk_mul_f32 v[68:69], v[64:65], s[22:23] op_sel_hi:[1,0]
	v_cvt_pk_bf16_f32 v65, v62, v63
	v_mul_lo_u32 v62, v77, s21
	v_cvt_pk_bf16_f32 v64, v74, v75
	v_cvt_pk_bf16_f32 v67, v68, v69
	v_add3_u32 v0, 0, v0, v62
	ds_write_b128 v0, v[64:67] offset:36864
	v_lshlrev_b32_e32 v64, 16, v58
	v_and_b32_e32 v65, 0xffff0000, v58
	v_lshlrev_b32_e32 v62, 16, v54
	v_and_b32_e32 v63, 0xffff0000, v54
	v_pk_mul_f32 v[64:65], v[30:31], v[64:65]
	v_lshlrev_b32_e32 v58, 16, v59
	v_pk_fma_f32 v[62:63], v[26:27], v[62:63], v[64:65]
	v_lshlrev_b32_e32 v64, 16, v50
	v_and_b32_e32 v65, 0xffff0000, v50
	v_pk_fma_f32 v[62:63], v[42:43], v[64:65], v[62:63]
	v_and_b32_e32 v59, 0xffff0000, v59
	v_mul_f32_e32 v50, 0xbfb8aa3b, v62
	v_exp_f32_e32 v50, v50
	v_lshlrev_b32_e32 v54, 16, v55
	v_and_b32_e32 v55, 0xffff0000, v55
	v_pk_mul_f32 v[58:59], v[32:33], v[58:59]
	v_add_f32_e32 v50, 1.0, v50
	v_rcp_f32_e32 v64, v50
	v_mul_f32_e32 v50, 0xbfb8aa3b, v63
	v_exp_f32_e32 v50, v50
	v_pk_fma_f32 v[54:55], v[28:29], v[54:55], v[58:59]
	v_lshlrev_b32_e32 v58, 16, v60
	v_and_b32_e32 v59, 0xffff0000, v60
	v_add_f32_e32 v50, 1.0, v50
	v_rcp_f32_e32 v65, v50
	v_lshlrev_b32_e32 v50, 16, v51
	v_and_b32_e32 v51, 0xffff0000, v51
	v_pk_fma_f32 v[50:51], v[44:45], v[50:51], v[54:55]
	v_pk_mul_f32 v[58:59], v[18:19], v[58:59]
	v_mul_f32_e32 v54, 0xbfb8aa3b, v50
	v_mul_f32_e32 v55, 0xbfb8aa3b, v51
	v_exp_f32_e32 v54, v54
	v_exp_f32_e32 v55, v55
	v_pk_mul_f32 v[62:63], v[62:63], v[64:65]
	v_mov_b32_e32 v74, 0
	v_add_f32_e32 v54, 1.0, v54
	v_add_f32_e32 v55, 1.0, v55
	v_rcp_f32_e32 v54, v54
	v_rcp_f32_e32 v55, v55
	v_pk_mul_f32 v[62:63], v[62:63], s[22:23] op_sel_hi:[1,0]
	v_mov_b32_e32 v75, 0
	v_pk_mul_f32 v[50:51], v[50:51], v[54:55]
	s_nop 0
	v_pk_mul_f32 v[54:55], v[50:51], s[22:23] op_sel_hi:[1,0]
	v_lshlrev_b32_e32 v50, 16, v56
	v_and_b32_e32 v51, 0xffff0000, v56
	v_pk_fma_f32 v[50:51], v[14:15], v[50:51], v[58:59]
	v_lshlrev_b32_e32 v58, 16, v52
	v_and_b32_e32 v59, 0xffff0000, v52
	v_pk_fma_f32 v[50:51], v[22:23], v[58:59], v[50:51]
	v_lshlrev_b32_e32 v56, 16, v61
	v_mul_f32_e32 v52, 0xbfb8aa3b, v50
	v_exp_f32_e32 v52, v52
	s_nop 0
	v_add_f32_e32 v52, 1.0, v52
	v_rcp_f32_e32 v58, v52
	v_mul_f32_e32 v52, 0xbfb8aa3b, v51
	v_exp_f32_e32 v52, v52
	s_nop 0
	v_add_f32_e32 v52, 1.0, v52
	v_rcp_f32_e32 v59, v52
	v_lshlrev_b32_e32 v52, 16, v53
	v_and_b32_e32 v53, 0xffff0000, v53
	v_pk_mul_f32 v[50:51], v[50:51], v[58:59]
	s_nop 0
	v_pk_mul_f32 v[58:59], v[50:51], s[22:23] op_sel_hi:[1,0]
	v_lshlrev_b32_e32 v50, 16, v57
	v_and_b32_e32 v51, 0xffff0000, v57
	v_and_b32_e32 v57, 0xffff0000, v61
	v_pk_mul_f32 v[56:57], v[20:21], v[56:57]
	s_nop 0
	v_pk_fma_f32 v[50:51], v[16:17], v[50:51], v[56:57]
	s_nop 0
	v_pk_fma_f32 v[50:51], v[24:25], v[52:53], v[50:51]
	s_nop 0
	v_mul_f32_e32 v52, 0xbfb8aa3b, v50
	v_mul_f32_e32 v53, 0xbfb8aa3b, v51
	v_exp_f32_e32 v52, v52
	v_exp_f32_e32 v53, v53
	v_add_f32_e32 v52, 1.0, v52
	v_add_f32_e32 v53, 1.0, v53
	v_rcp_f32_e32 v52, v52
	v_rcp_f32_e32 v53, v53
	s_nop 0
	v_pk_mul_f32 v[50:51], v[50:51], v[52:53]
	s_nop 0
	v_pk_mul_f32 v[56:57], v[50:51], s[22:23] op_sel_hi:[1,0]
	v_cvt_pk_bf16_f32 v50, v62, v63
	v_cvt_pk_bf16_f32 v51, v54, v55
	v_cvt_pk_bf16_f32 v52, v58, v59
	v_cvt_pk_bf16_f32 v53, v56, v57
	ds_write_b128 v0, v[50:53] offset:46080
	v_lshlrev_b32_e32 v52, 16, v46
	v_and_b32_e32 v53, 0xffff0000, v46
	v_lshlrev_b32_e32 v50, 16, v38
	v_and_b32_e32 v51, 0xffff0000, v38
	v_pk_mul_f32 v[52:53], v[30:31], v[52:53]
	v_lshlrev_b32_e32 v46, 16, v47
	v_pk_fma_f32 v[50:51], v[26:27], v[50:51], v[52:53]
	v_lshlrev_b32_e32 v52, 16, v34
	v_and_b32_e32 v53, 0xffff0000, v34
	v_pk_fma_f32 v[50:51], v[42:43], v[52:53], v[50:51]
	v_and_b32_e32 v47, 0xffff0000, v47
	v_mul_f32_e32 v34, 0xbfb8aa3b, v50
	v_exp_f32_e32 v34, v34
	v_lshlrev_b32_e32 v38, 16, v39
	v_and_b32_e32 v39, 0xffff0000, v39
	v_pk_mul_f32 v[46:47], v[32:33], v[46:47]
	v_add_f32_e32 v34, 1.0, v34
	v_rcp_f32_e32 v52, v34
	v_mul_f32_e32 v34, 0xbfb8aa3b, v51
	v_exp_f32_e32 v34, v34
	v_pk_fma_f32 v[38:39], v[28:29], v[38:39], v[46:47]
	v_lshlrev_b32_e32 v46, 16, v48
	v_and_b32_e32 v47, 0xffff0000, v48
	v_add_f32_e32 v34, 1.0, v34
	v_rcp_f32_e32 v53, v34
	v_lshlrev_b32_e32 v34, 16, v35
	v_and_b32_e32 v35, 0xffff0000, v35
	v_pk_fma_f32 v[34:35], v[44:45], v[34:35], v[38:39]
	v_pk_mul_f32 v[46:47], v[18:19], v[46:47]
	v_mul_f32_e32 v38, 0xbfb8aa3b, v34
	v_mul_f32_e32 v39, 0xbfb8aa3b, v35
	v_exp_f32_e32 v38, v38
	v_exp_f32_e32 v39, v39
	v_pk_mul_f32 v[50:51], v[50:51], v[52:53]
	v_add_f32_e32 v38, 1.0, v38
	v_add_f32_e32 v39, 1.0, v39
	v_rcp_f32_e32 v38, v38
	v_rcp_f32_e32 v39, v39
	v_pk_mul_f32 v[50:51], v[50:51], s[22:23] op_sel_hi:[1,0]
	v_pk_mul_f32 v[34:35], v[34:35], v[38:39]
	s_nop 0
	v_pk_mul_f32 v[38:39], v[34:35], s[22:23] op_sel_hi:[1,0]
	v_lshlrev_b32_e32 v34, 16, v40
	v_and_b32_e32 v35, 0xffff0000, v40
	v_pk_fma_f32 v[34:35], v[14:15], v[34:35], v[46:47]
	v_lshlrev_b32_e32 v46, 16, v36
	v_and_b32_e32 v47, 0xffff0000, v36
	v_pk_fma_f32 v[34:35], v[22:23], v[46:47], v[34:35]
	v_lshlrev_b32_e32 v40, 16, v49
	v_mul_f32_e32 v36, 0xbfb8aa3b, v34
	v_exp_f32_e32 v36, v36
	s_nop 0
	v_add_f32_e32 v36, 1.0, v36
	v_rcp_f32_e32 v46, v36
	v_mul_f32_e32 v36, 0xbfb8aa3b, v35
	v_exp_f32_e32 v36, v36
	s_nop 0
	v_add_f32_e32 v36, 1.0, v36
	v_rcp_f32_e32 v47, v36
	v_lshlrev_b32_e32 v36, 16, v37
	v_and_b32_e32 v37, 0xffff0000, v37
	v_pk_mul_f32 v[34:35], v[34:35], v[46:47]
	s_nop 0
	v_pk_mul_f32 v[46:47], v[34:35], s[22:23] op_sel_hi:[1,0]
	v_lshlrev_b32_e32 v34, 16, v41
	v_and_b32_e32 v35, 0xffff0000, v41
	v_and_b32_e32 v41, 0xffff0000, v49
	v_pk_mul_f32 v[40:41], v[20:21], v[40:41]
	s_nop 0
	v_pk_fma_f32 v[34:35], v[16:17], v[34:35], v[40:41]
	s_nop 0
	v_pk_fma_f32 v[34:35], v[24:25], v[36:37], v[34:35]
	s_nop 0
	v_mul_f32_e32 v36, 0xbfb8aa3b, v34
	v_mul_f32_e32 v37, 0xbfb8aa3b, v35
	v_exp_f32_e32 v36, v36
	v_exp_f32_e32 v37, v37
	v_add_f32_e32 v36, 1.0, v36
	v_add_f32_e32 v37, 1.0, v37
	v_rcp_f32_e32 v36, v36
	v_rcp_f32_e32 v37, v37
	s_nop 0
	v_pk_mul_f32 v[34:35], v[34:35], v[36:37]
	s_nop 0
	v_pk_mul_f32 v[40:41], v[34:35], s[22:23] op_sel_hi:[1,0]
	v_cvt_pk_bf16_f32 v34, v50, v51
	v_cvt_pk_bf16_f32 v35, v38, v39
	v_cvt_pk_bf16_f32 v36, v46, v47
	v_cvt_pk_bf16_f32 v37, v40, v41
	ds_write_b128 v0, v[34:37] offset:55296
	v_lshlrev_b32_e32 v36, 16, v10
	v_and_b32_e32 v37, 0xffff0000, v10
	v_lshlrev_b32_e32 v34, 16, v6
	v_and_b32_e32 v35, 0xffff0000, v6
	v_pk_mul_f32 v[30:31], v[30:31], v[36:37]
	v_lshlrev_b32_e32 v10, 16, v11
	v_pk_fma_f32 v[26:27], v[26:27], v[34:35], v[30:31]
	v_lshlrev_b32_e32 v30, 16, v2
	v_and_b32_e32 v31, 0xffff0000, v2
	v_pk_fma_f32 v[26:27], v[42:43], v[30:31], v[26:27]
	v_and_b32_e32 v11, 0xffff0000, v11
	v_mul_f32_e32 v2, 0xbfb8aa3b, v26
	v_exp_f32_e32 v2, v2
	v_lshlrev_b32_e32 v6, 16, v7
	v_and_b32_e32 v7, 0xffff0000, v7
	v_pk_mul_f32 v[10:11], v[32:33], v[10:11]
	v_add_f32_e32 v2, 1.0, v2
	v_rcp_f32_e32 v30, v2
	v_mul_f32_e32 v2, 0xbfb8aa3b, v27
	v_exp_f32_e32 v2, v2
	v_pk_fma_f32 v[6:7], v[28:29], v[6:7], v[10:11]
	v_lshlrev_b32_e32 v10, 16, v12
	v_and_b32_e32 v11, 0xffff0000, v12
	v_add_f32_e32 v2, 1.0, v2
	v_rcp_f32_e32 v31, v2
	v_lshlrev_b32_e32 v2, 16, v3
	v_and_b32_e32 v3, 0xffff0000, v3
	v_pk_fma_f32 v[2:3], v[44:45], v[2:3], v[6:7]
	v_pk_mul_f32 v[10:11], v[18:19], v[10:11]
	v_mul_f32_e32 v6, 0xbfb8aa3b, v2
	v_mul_f32_e32 v7, 0xbfb8aa3b, v3
	v_exp_f32_e32 v6, v6
	v_exp_f32_e32 v7, v7
	v_pk_mul_f32 v[26:27], v[26:27], v[30:31]
	v_mov_b32_e32 v50, 0
	v_add_f32_e32 v6, 1.0, v6
	v_add_f32_e32 v7, 1.0, v7
	v_rcp_f32_e32 v6, v6
	v_rcp_f32_e32 v7, v7
	v_pk_mul_f32 v[26:27], v[26:27], s[22:23] op_sel_hi:[1,0]
	v_pk_mul_f32 v[2:3], v[2:3], v[6:7]
	s_nop 0
	v_pk_mul_f32 v[6:7], v[2:3], s[22:23] op_sel_hi:[1,0]
	v_lshlrev_b32_e32 v2, 16, v8
	v_and_b32_e32 v3, 0xffff0000, v8
	v_pk_fma_f32 v[2:3], v[14:15], v[2:3], v[10:11]
	v_lshlrev_b32_e32 v10, 16, v4
	v_and_b32_e32 v11, 0xffff0000, v4
	v_pk_fma_f32 v[2:3], v[22:23], v[10:11], v[2:3]
	v_lshlrev_b32_e32 v8, 16, v13
	v_mul_f32_e32 v4, 0xbfb8aa3b, v2
	v_exp_f32_e32 v4, v4
	v_mov_b64_e32 v[14:15], s[50:51]
	v_add_f32_e32 v4, 1.0, v4
	v_rcp_f32_e32 v10, v4
	v_mul_f32_e32 v4, 0xbfb8aa3b, v3
	v_exp_f32_e32 v4, v4
	s_nop 0
	v_add_f32_e32 v4, 1.0, v4
	v_rcp_f32_e32 v11, v4
	v_lshlrev_b32_e32 v4, 16, v5
	v_and_b32_e32 v5, 0xffff0000, v5
	v_pk_mul_f32 v[2:3], v[2:3], v[10:11]
	s_nop 0
	v_pk_mul_f32 v[10:11], v[2:3], s[22:23] op_sel_hi:[1,0]
	v_lshlrev_b32_e32 v2, 16, v9
	v_and_b32_e32 v3, 0xffff0000, v9
	v_and_b32_e32 v9, 0xffff0000, v13
	v_pk_mul_f32 v[8:9], v[20:21], v[8:9]
	s_nop 0
	v_pk_fma_f32 v[2:3], v[16:17], v[2:3], v[8:9]
	s_nop 0
	v_pk_fma_f32 v[2:3], v[24:25], v[4:5], v[2:3]
	s_nop 0
	v_mul_f32_e32 v4, 0xbfb8aa3b, v2
	v_mul_f32_e32 v5, 0xbfb8aa3b, v3
	v_exp_f32_e32 v4, v4
	v_exp_f32_e32 v5, v5
	v_add_f32_e32 v4, 1.0, v4
	v_add_f32_e32 v5, 1.0, v5
	v_rcp_f32_e32 v4, v4
	v_rcp_f32_e32 v5, v5
	s_nop 0
	v_pk_mul_f32 v[2:3], v[2:3], v[4:5]
	s_nop 0
	v_pk_mul_f32 v[8:9], v[2:3], s[22:23] op_sel_hi:[1,0]
	v_cvt_pk_bf16_f32 v2, v26, v27
	v_cvt_pk_bf16_f32 v3, v6, v7
	v_cvt_pk_bf16_f32 v4, v10, v11
	v_cvt_pk_bf16_f32 v5, v8, v9
	ds_write_b128 v0, v[2:5] offset:64512
	v_mov_b32_e32 v0, v192
	s_nop 0
	v_ashrrev_i32_e32 v18, 4, v0
	v_lshlrev_b32_e32 v0, 4, v0
	v_and_b32_e32 v0, 0xf0, v0
	s_lshl_b32 s0, s67, 8
	s_lshl_b32 s1, s78, 6
	s_or_b32 s0, s1, s0
	s_or_b32 s4, s0, s66
	s_ashr_i32 s5, s4, 31
	s_lshl_b64 s[0:1], s[4:5], 2
	v_mul_lo_u32 v18, v18, s21
	s_add_u32 s0, s46, s0
	v_add3_u32 v0, s68, v0, v18
	s_addc_u32 s1, s47, s1
	s_waitcnt vmcnt(3)
	ds_write_b128 v0, v[104:107]
	s_waitcnt vmcnt(2)
	ds_write_b128 v0, v[108:111] offset:9216
	s_waitcnt vmcnt(1)
	ds_write_b128 v0, v[112:115] offset:18432
	s_waitcnt vmcnt(0)
	ds_write_b128 v0, v[116:119] offset:27648
	s_waitcnt lgkmcnt(0)
	s_barrier
	global_load_dword v22, v195, s[0:1]
	v_or_b32_e32 v0, v96, v94
	v_mul_lo_u32 v2, v0, s21
	v_add_u32_e32 v51, 0, v2
	v_and_b32_e32 v2, 48, v76
	v_add_u32_e32 v3, v51, v2
	v_add_u32_e32 v91, 0, v2
	ds_read_b128 v[14:17], v3
	ds_read_b128 v[10:13], v3 offset:64
	ds_read_b128 v[6:9], v3 offset:128
	ds_read_b128 v[2:5], v3 offset:192
	v_lshl_add_u32 v52, v0, 2, 0
	v_add_u32_e32 v18, 0x1b200, v52
	ds_read_b32 v87, v18
	v_cmp_lt_i32_e64 s[0:1], -1, v86
	v_mad_u32_u24 v23, v94, s21, v91
	s_and_saveexec_b64 s[42:43], s[0:1]
	s_cbranch_execz .LBB0_773
	ds_read_b128 v[18:21], v23 offset:36864
	ds_read_b128 v[24:27], v23 offset:36928
	v_cmp_le_i32_e32 vcc, v95, v0
	s_waitcnt lgkmcnt(1)
	v_mfma_f32_16x16x32_bf16 v[18:21], v[18:21], v[14:17], 0
	s_waitcnt lgkmcnt(0)
	v_mfma_f32_16x16x32_bf16 v[18:21], v[24:27], v[10:13], v[18:21]
	ds_read_b128 v[24:27], v23 offset:36992
	s_waitcnt lgkmcnt(0)
	v_mfma_f32_16x16x32_bf16 v[18:21], v[24:27], v[6:9], v[18:21]
	ds_read_b128 v[24:27], v23 offset:37056
	s_waitcnt lgkmcnt(0)
	v_mfma_f32_16x16x32_bf16 v[18:21], v[24:27], v[2:5], v[18:21]
	v_mov_b32_e32 v24, 0
	v_mov_b32_e32 v25, 0
	s_and_saveexec_b64 s[44:45], vcc
	s_cbranch_execz .LBB0_766
	v_lshl_add_u32 v25, v95, 2, 0
	v_add_u32_e32 v25, 0x1b000, v25
	ds_read_b32 v25, v25
	s_waitcnt lgkmcnt(0)
	v_sub_f32_e32 v25, v25, v87
	v_mul_f32_e32 v25, 0x3fb8aa3b, v25
	v_exp_f32_e32 v25, v25
